# add: P10 epilogue warms the unit's E tile (same access pattern, results unused) before its 32 serialized load steps
# baseline (speedup 1.0000x reference)
.LBB0_1604:
	s_lshl_b32 s31, s46, 8
	v_lshl_add_u32 v202, s44, 8, v216
	s_cmp_lt_i32 s16, 0
	s_mov_b64 s[44:45], -1
	v_ashrrev_i32_e32 v203, 31, v202
	s_cbranch_scc0 .LBB0_1607
	v_add_u32_e32 v204, s31, v214
	v_lshlrev_b64 v[0:1], 2, v[202:203]
	v_ashrrev_i32_e32 v205, 31, v204
	v_lshl_add_u64 v[8:9], s[20:21], 0, v[0:1]
	v_lshl_add_u64 v[2:3], v[204:205], 3, s[0:1]
	global_load_dwordx4 v[176:179], v[8:9], off
	v_lshl_add_u64 v[10:11], s[22:23], 0, v[0:1]
	global_load_dwordx2 v[206:207], v[2:3], off
	global_load_dwordx4 v[188:191], v[10:11], off
	v_lshlrev_b64 v[2:3], 12, v[204:205]
	v_lshl_add_u64 v[208:209], v[2:3], 0, v[202:203]
	v_lshlrev_b64 v[2:3], 1, v[208:209]
	v_lshl_add_u64 v[210:211], s[12:13], 0, v[2:3]
	global_load_dwordx2 v[222:223], v[210:211], off
	v_lshl_add_u64 v[212:213], s[18:19], 0, v[2:3]
	global_load_dwordx2 v[224:225], v[212:213], off
	s_mov_b64 s[98:99], 0x20000
	s_mov_b64 s[100:101], 0xa0000
	global_load_dwordx2 v[238:239], v[212:213], off offset:256
	v_lshl_add_u64 v[240:241], v[212:213], 0, s[98:99]
	global_load_dwordx2 v[238:239], v[240:241], off
	global_load_dwordx2 v[238:239], v[240:241], off offset:256
	v_lshl_add_u64 v[240:241], v[240:241], 0, s[98:99]
	global_load_dwordx2 v[238:239], v[240:241], off
	global_load_dwordx2 v[238:239], v[240:241], off offset:256
	v_lshl_add_u64 v[240:241], v[240:241], 0, s[98:99]
	global_load_dwordx2 v[238:239], v[240:241], off
	global_load_dwordx2 v[238:239], v[240:241], off offset:256
	v_lshl_add_u64 v[240:241], v[240:241], 0, s[100:101]
	global_load_dwordx2 v[238:239], v[240:241], off
	global_load_dwordx2 v[238:239], v[240:241], off offset:256
	v_lshl_add_u64 v[240:241], v[240:241], 0, s[98:99]
	global_load_dwordx2 v[238:239], v[240:241], off
	global_load_dwordx2 v[238:239], v[240:241], off offset:256
	v_lshl_add_u64 v[240:241], v[240:241], 0, s[98:99]
	global_load_dwordx2 v[238:239], v[240:241], off
	global_load_dwordx2 v[238:239], v[240:241], off offset:256
	v_lshl_add_u64 v[240:241], v[240:241], 0, s[98:99]
	global_load_dwordx2 v[238:239], v[240:241], off
	global_load_dwordx2 v[238:239], v[240:241], off offset:256
	v_lshl_add_u64 v[2:3], s[8:9], 0, v[0:1]
	v_lshl_add_u64 v[4:5], s[10:11], 0, v[0:1]
	global_load_dwordx4 v[180:183], v[4:5], off
	global_load_dwordx4 v[184:187], v[2:3], off
	global_load_dwordx4 v[160:163], v[2:3], off offset:64
	global_load_dwordx4 v[164:167], v[4:5], off offset:64
	global_load_dwordx4 v[172:175], v[8:9], off offset:64
	global_load_dwordx4 v[168:171], v[10:11], off offset:64
	global_load_dwordx4 v[16:19], v[2:3], off offset:512
	s_nop 0
	global_load_dwordx4 v[0:3], v[2:3], off offset:576
	s_nop 0
	global_load_dwordx4 v[20:23], v[4:5], off offset:512
	s_nop 0
	global_load_dwordx4 v[4:7], v[4:5], off offset:576
	s_nop 0
	global_load_dwordx4 v[28:31], v[8:9], off offset:512
	global_load_dwordx4 v[12:15], v[8:9], off offset:576
	global_load_dwordx4 v[24:27], v[10:11], off offset:512
	s_nop 0
	global_load_dwordx4 v[8:11], v[10:11], off offset:576
	v_lshl_add_u64 v[208:209], v[208:209], 2, s[14:15]
	s_waitcnt vmcnt(0)
	v_pk_mul_f32 v[226:227], v[178:179], v[206:207] op_sel_hi:[1,0]
	v_pk_mul_f32 v[228:229], v[176:177], v[206:207] op_sel_hi:[1,0]
	v_pk_fma_f32 v[226:227], v[158:159], s[26:27], v[226:227] op_sel_hi:[1,0,1] neg_lo:[0,0,1] neg_hi:[0,0,1]
	v_pk_fma_f32 v[228:229], v[156:157], s[26:27], v[228:229] op_sel_hi:[1,0,1] neg_lo:[0,0,1] neg_hi:[0,0,1]
	v_pk_fma_f32 v[226:227], v[206:207], v[226:227], v[190:191] op_sel:[1,0,0]
	v_pk_fma_f32 v[228:229], v[206:207], v[228:229], v[188:189] op_sel:[1,0,0]
	v_lshlrev_b32_e32 v205, 16, v222
	v_and_b32_e32 v221, 0xffff0000, v222
	v_lshlrev_b32_e32 v230, 16, v223
	v_and_b32_e32 v231, 0xffff0000, v223
	v_mul_f32_e32 v232, 0xbfb8aa3b, v228
	v_mul_f32_e32 v233, 0xbfb8aa3b, v229
	v_mul_f32_e32 v234, 0xbfb8aa3b, v226
	v_mul_f32_e32 v235, 0xbfb8aa3b, v227
	v_sub_f32_e32 v227, v231, v206
	v_sub_f32_e32 v226, v230, v206
	v_sub_f32_e32 v229, v221, v206
	v_sub_f32_e32 v228, v205, v206
	v_exp_f32_e32 v205, v232
	v_exp_f32_e32 v221, v233
	v_exp_f32_e32 v230, v234
	v_exp_f32_e32 v231, v235
	v_add_f32_e32 v205, 1.0, v205
	v_add_f32_e32 v221, 1.0, v221
	v_add_f32_e32 v232, 1.0, v230
	v_add_f32_e32 v233, 1.0, v231
	v_rcp_f32_e32 v230, v205
	v_rcp_f32_e32 v231, v221
	v_rcp_f32_e32 v232, v232
	v_rcp_f32_e32 v233, v233
	v_pk_mul_f32 v[228:229], v[206:207], v[228:229] op_sel:[1,0]
	v_pk_mul_f32 v[226:227], v[206:207], v[226:227] op_sel:[1,0]
	v_lshlrev_b32_e32 v222, 16, v224
	v_and_b32_e32 v223, 0xffff0000, v224
	v_lshlrev_b32_e32 v224, 16, v225
	v_and_b32_e32 v225, 0xffff0000, v225
	v_pk_fma_f32 v[226:227], v[186:187], v[226:227], v[182:183]
	v_pk_fma_f32 v[228:229], v[184:185], v[228:229], v[180:181]
	v_pk_fma_f32 v[224:225], v[232:233], v[224:225], v[226:227]
	v_pk_fma_f32 v[222:223], v[230:231], v[222:223], v[228:229]
	global_store_dwordx4 v[208:209], v[222:225], off
	global_load_dwordx2 v[222:223], v[210:211], off offset:32
	s_nop 0
	global_load_dwordx2 v[224:225], v[212:213], off offset:32
	v_pk_mul_f32 v[226:227], v[174:175], v[206:207] op_sel_hi:[1,0]
	v_pk_mul_f32 v[228:229], v[172:173], v[206:207] op_sel_hi:[1,0]
	v_pk_fma_f32 v[226:227], v[154:155], s[26:27], v[226:227] op_sel_hi:[1,0,1] neg_lo:[0,0,1] neg_hi:[0,0,1]
	v_pk_fma_f32 v[228:229], v[152:153], s[26:27], v[228:229] op_sel_hi:[1,0,1] neg_lo:[0,0,1] neg_hi:[0,0,1]
	v_pk_fma_f32 v[226:227], v[206:207], v[226:227], v[170:171] op_sel:[1,0,0]
	v_pk_fma_f32 v[228:229], v[206:207], v[228:229], v[168:169] op_sel:[1,0,0]
	v_mul_f32_e32 v226, 0xbfb8aa3b, v226
	v_mul_f32_e32 v205, 0xbfb8aa3b, v228
	v_mul_f32_e32 v221, 0xbfb8aa3b, v229
	v_mul_f32_e32 v227, 0xbfb8aa3b, v227
	v_exp_f32_e32 v205, v205
	v_exp_f32_e32 v221, v221
	v_exp_f32_e32 v226, v226
	v_exp_f32_e32 v227, v227
	v_add_f32_e32 v205, 1.0, v205
	v_add_f32_e32 v221, 1.0, v221
	v_add_f32_e32 v228, 1.0, v226
	v_add_f32_e32 v229, 1.0, v227
	v_rcp_f32_e32 v226, v205
	v_rcp_f32_e32 v227, v221
	v_rcp_f32_e32 v228, v228
	v_rcp_f32_e32 v229, v229
	s_waitcnt vmcnt(1)
	v_lshlrev_b32_e32 v205, 16, v222
	v_and_b32_e32 v221, 0xffff0000, v222
	v_lshlrev_b32_e32 v230, 16, v223
	v_and_b32_e32 v231, 0xffff0000, v223
	v_sub_f32_e32 v231, v231, v206
	v_sub_f32_e32 v230, v230, v206
	v_sub_f32_e32 v233, v221, v206
	v_sub_f32_e32 v232, v205, v206
	v_pk_mul_f32 v[232:233], v[206:207], v[232:233] op_sel:[1,0]
	v_pk_mul_f32 v[230:231], v[206:207], v[230:231] op_sel:[1,0]
	s_waitcnt vmcnt(0)
	v_lshlrev_b32_e32 v222, 16, v224
	v_and_b32_e32 v223, 0xffff0000, v224
	v_lshlrev_b32_e32 v224, 16, v225
	v_and_b32_e32 v225, 0xffff0000, v225
	v_pk_fma_f32 v[230:231], v[162:163], v[230:231], v[166:167]
	v_pk_fma_f32 v[232:233], v[160:161], v[232:233], v[164:165]
	v_pk_fma_f32 v[224:225], v[228:229], v[224:225], v[230:231]
	v_pk_fma_f32 v[222:223], v[226:227], v[222:223], v[232:233]
	global_store_dwordx4 v[208:209], v[222:225], off offset:64
	global_load_dwordx2 v[222:223], v[210:211], off offset:256
	s_nop 0
	global_load_dwordx2 v[224:225], v[212:213], off offset:256
	v_pk_mul_f32 v[226:227], v[30:31], v[206:207] op_sel_hi:[1,0]
	v_pk_mul_f32 v[228:229], v[28:29], v[206:207] op_sel_hi:[1,0]
	v_pk_fma_f32 v[226:227], v[146:147], s[26:27], v[226:227] op_sel_hi:[1,0,1] neg_lo:[0,0,1] neg_hi:[0,0,1]
	v_pk_fma_f32 v[228:229], v[144:145], s[26:27], v[228:229] op_sel_hi:[1,0,1] neg_lo:[0,0,1] neg_hi:[0,0,1]
	v_pk_fma_f32 v[226:227], v[206:207], v[226:227], v[26:27] op_sel:[1,0,0]
	v_pk_fma_f32 v[228:229], v[206:207], v[228:229], v[24:25] op_sel:[1,0,0]
	v_mul_f32_e32 v226, 0xbfb8aa3b, v226
	v_mul_f32_e32 v205, 0xbfb8aa3b, v228
	v_mul_f32_e32 v221, 0xbfb8aa3b, v229
	v_mul_f32_e32 v227, 0xbfb8aa3b, v227
	v_exp_f32_e32 v205, v205
	v_exp_f32_e32 v221, v221
	v_exp_f32_e32 v226, v226
	v_exp_f32_e32 v227, v227
	v_add_f32_e32 v205, 1.0, v205
	v_add_f32_e32 v221, 1.0, v221
	v_add_f32_e32 v228, 1.0, v226
	v_add_f32_e32 v229, 1.0, v227
	v_rcp_f32_e32 v226, v205
	v_rcp_f32_e32 v227, v221
	v_rcp_f32_e32 v228, v228
	v_rcp_f32_e32 v229, v229
	s_waitcnt vmcnt(1)
	v_lshlrev_b32_e32 v205, 16, v222
	v_and_b32_e32 v221, 0xffff0000, v222
	v_lshlrev_b32_e32 v230, 16, v223
	v_and_b32_e32 v231, 0xffff0000, v223
	v_sub_f32_e32 v231, v231, v206
	v_sub_f32_e32 v230, v230, v206
	v_sub_f32_e32 v233, v221, v206
	v_sub_f32_e32 v232, v205, v206
	v_pk_mul_f32 v[232:233], v[206:207], v[232:233] op_sel:[1,0]
	v_pk_mul_f32 v[230:231], v[206:207], v[230:231] op_sel:[1,0]
	s_waitcnt vmcnt(0)
	v_lshlrev_b32_e32 v222, 16, v224
	v_and_b32_e32 v223, 0xffff0000, v224
	v_lshlrev_b32_e32 v224, 16, v225
	v_and_b32_e32 v225, 0xffff0000, v225
	v_pk_fma_f32 v[230:231], v[18:19], v[230:231], v[22:23]
	v_pk_fma_f32 v[232:233], v[16:17], v[232:233], v[20:21]
	v_pk_fma_f32 v[224:225], v[228:229], v[224:225], v[230:231]
	v_pk_fma_f32 v[222:223], v[226:227], v[222:223], v[232:233]
	global_store_dwordx4 v[208:209], v[222:225], off offset:512
	global_load_dwordx2 v[222:223], v[210:211], off offset:288
	s_nop 0
	global_load_dwordx2 v[212:213], v[212:213], off offset:288
	v_pk_mul_f32 v[224:225], v[14:15], v[206:207] op_sel_hi:[1,0]
	v_pk_mul_f32 v[232:233], v[12:13], v[206:207] op_sel_hi:[1,0]
	v_pk_fma_f32 v[224:225], v[138:139], s[26:27], v[224:225] op_sel_hi:[1,0,1] neg_lo:[0,0,1] neg_hi:[0,0,1]
	v_pk_fma_f32 v[232:233], v[136:137], s[26:27], v[232:233] op_sel_hi:[1,0,1] neg_lo:[0,0,1] neg_hi:[0,0,1]
	v_pk_fma_f32 v[224:225], v[206:207], v[224:225], v[10:11] op_sel:[1,0,0]
	v_pk_fma_f32 v[232:233], v[206:207], v[232:233], v[8:9] op_sel:[1,0,0]
	v_mul_f32_e32 v224, 0xbfb8aa3b, v224
	v_mul_f32_e32 v205, 0xbfb8aa3b, v232
	v_mul_f32_e32 v221, 0xbfb8aa3b, v233
	v_mul_f32_e32 v225, 0xbfb8aa3b, v225
	v_exp_f32_e32 v205, v205
	v_exp_f32_e32 v221, v221
	v_exp_f32_e32 v224, v224
	v_exp_f32_e32 v225, v225
	v_add_f32_e32 v205, 1.0, v205
	v_add_f32_e32 v221, 1.0, v221
	v_add_f32_e32 v232, 1.0, v224
	v_add_f32_e32 v233, 1.0, v225
	v_or_b32_e32 v226, 16, v204
	v_rcp_f32_e32 v224, v205
	v_rcp_f32_e32 v225, v221
	v_rcp_f32_e32 v232, v232
	v_rcp_f32_e32 v233, v233
	v_ashrrev_i32_e32 v227, 31, v226
	v_lshlrev_b64 v[210:211], 12, v[226:227]
	v_lshl_add_u64 v[228:229], v[210:211], 0, v[202:203]
	v_lshlrev_b64 v[230:231], 1, v[228:229]
	v_lshl_add_u64 v[210:211], s[12:13], 0, v[230:231]
	s_waitcnt vmcnt(1)
	v_lshlrev_b32_e32 v205, 16, v222
	v_and_b32_e32 v221, 0xffff0000, v222
	v_lshlrev_b32_e32 v234, 16, v223
	v_and_b32_e32 v235, 0xffff0000, v223
	v_sub_f32_e32 v235, v235, v206
	v_sub_f32_e32 v234, v234, v206
	v_sub_f32_e32 v237, v221, v206
	v_sub_f32_e32 v236, v205, v206
	v_pk_mul_f32 v[236:237], v[206:207], v[236:237] op_sel:[1,0]
	v_pk_mul_f32 v[206:207], v[206:207], v[234:235] op_sel:[1,0]
	s_waitcnt vmcnt(0)
	v_lshlrev_b32_e32 v222, 16, v212
	v_and_b32_e32 v223, 0xffff0000, v212
	v_lshlrev_b32_e32 v212, 16, v213
	v_and_b32_e32 v213, 0xffff0000, v213
	v_pk_fma_f32 v[206:207], v[2:3], v[206:207], v[6:7]
	v_pk_fma_f32 v[234:235], v[0:1], v[236:237], v[4:5]
	s_nop 0
	v_pk_fma_f32 v[222:223], v[224:225], v[222:223], v[234:235]
	v_pk_fma_f32 v[224:225], v[232:233], v[212:213], v[206:207]
	global_store_dwordx4 v[208:209], v[222:225], off offset:576
	v_lshl_add_u64 v[206:207], v[226:227], 3, s[0:1]
	v_lshl_add_u64 v[212:213], s[18:19], 0, v[230:231]
	global_load_dwordx2 v[222:223], v[210:211], off
	global_load_dwordx2 v[224:225], v[212:213], off
	s_nop 0
	global_load_dwordx2 v[206:207], v[206:207], off
	v_lshl_add_u64 v[208:209], v[228:229], 2, s[14:15]
	s_waitcnt vmcnt(1)
	v_lshlrev_b32_e32 v228, 16, v224
	v_lshlrev_b32_e32 v205, 16, v222
	v_and_b32_e32 v221, 0xffff0000, v222
	v_lshlrev_b32_e32 v230, 16, v223
	v_and_b32_e32 v231, 0xffff0000, v223
	s_waitcnt vmcnt(0)
	v_pk_mul_f32 v[222:223], v[178:179], v[206:207] op_sel_hi:[1,0]
	v_pk_mul_f32 v[226:227], v[176:177], v[206:207] op_sel_hi:[1,0]
	v_pk_fma_f32 v[222:223], v[150:151], s[26:27], v[222:223] op_sel_hi:[1,0,1] neg_lo:[0,0,1] neg_hi:[0,0,1]
	v_pk_fma_f32 v[226:227], v[148:149], s[26:27], v[226:227] op_sel_hi:[1,0,1] neg_lo:[0,0,1] neg_hi:[0,0,1]
	v_pk_fma_f32 v[222:223], v[206:207], v[222:223], v[190:191] op_sel:[1,0,0]
	v_pk_fma_f32 v[226:227], v[206:207], v[226:227], v[188:189] op_sel:[1,0,0]
	v_sub_f32_e32 v233, v221, v206
	v_sub_f32_e32 v232, v205, v206
	v_mul_f32_e32 v205, 0xbfb8aa3b, v226
	v_mul_f32_e32 v221, 0xbfb8aa3b, v227
	v_mul_f32_e32 v222, 0xbfb8aa3b, v222
	v_mul_f32_e32 v223, 0xbfb8aa3b, v223
	v_exp_f32_e32 v205, v205
	v_exp_f32_e32 v221, v221
	v_exp_f32_e32 v222, v222
	v_exp_f32_e32 v223, v223
	v_add_f32_e32 v205, 1.0, v205
	v_add_f32_e32 v221, 1.0, v221
	v_add_f32_e32 v226, 1.0, v222
	v_add_f32_e32 v227, 1.0, v223
	v_rcp_f32_e32 v222, v205
	v_rcp_f32_e32 v223, v221
	v_rcp_f32_e32 v226, v226
	v_rcp_f32_e32 v227, v227
	v_sub_f32_e32 v231, v231, v206
	v_sub_f32_e32 v230, v230, v206
	v_pk_mul_f32 v[232:233], v[206:207], v[232:233] op_sel:[1,0]
	v_pk_mul_f32 v[230:231], v[206:207], v[230:231] op_sel:[1,0]
	v_and_b32_e32 v229, 0xffff0000, v224
	v_lshlrev_b32_e32 v224, 16, v225
	v_and_b32_e32 v225, 0xffff0000, v225
	v_pk_fma_f32 v[230:231], v[186:187], v[230:231], v[182:183]
	v_pk_fma_f32 v[232:233], v[184:185], v[232:233], v[180:181]
	v_pk_fma_f32 v[224:225], v[226:227], v[224:225], v[230:231]
	v_pk_fma_f32 v[222:223], v[222:223], v[228:229], v[232:233]
	global_store_dwordx4 v[208:209], v[222:225], off
	global_load_dwordx2 v[222:223], v[210:211], off offset:32
	s_nop 0
	global_load_dwordx2 v[224:225], v[212:213], off offset:32
	v_pk_mul_f32 v[226:227], v[174:175], v[206:207] op_sel_hi:[1,0]
	v_pk_mul_f32 v[228:229], v[172:173], v[206:207] op_sel_hi:[1,0]
	v_pk_fma_f32 v[226:227], v[142:143], s[26:27], v[226:227] op_sel_hi:[1,0,1] neg_lo:[0,0,1] neg_hi:[0,0,1]
	v_pk_fma_f32 v[228:229], v[140:141], s[26:27], v[228:229] op_sel_hi:[1,0,1] neg_lo:[0,0,1] neg_hi:[0,0,1]
	v_pk_fma_f32 v[226:227], v[206:207], v[226:227], v[170:171] op_sel:[1,0,0]
	v_pk_fma_f32 v[228:229], v[206:207], v[228:229], v[168:169] op_sel:[1,0,0]
	v_mul_f32_e32 v226, 0xbfb8aa3b, v226
	v_mul_f32_e32 v205, 0xbfb8aa3b, v228
	v_mul_f32_e32 v221, 0xbfb8aa3b, v229
	v_mul_f32_e32 v227, 0xbfb8aa3b, v227
	v_exp_f32_e32 v205, v205
	v_exp_f32_e32 v221, v221
	v_exp_f32_e32 v226, v226
	v_exp_f32_e32 v227, v227
	v_add_f32_e32 v205, 1.0, v205
	v_add_f32_e32 v221, 1.0, v221
	v_add_f32_e32 v228, 1.0, v226
	v_add_f32_e32 v229, 1.0, v227
	v_rcp_f32_e32 v226, v205
	v_rcp_f32_e32 v227, v221
	v_rcp_f32_e32 v228, v228
	v_rcp_f32_e32 v229, v229
	s_waitcnt vmcnt(1)
	v_lshlrev_b32_e32 v205, 16, v222
	v_and_b32_e32 v221, 0xffff0000, v222
	v_lshlrev_b32_e32 v230, 16, v223
	v_and_b32_e32 v231, 0xffff0000, v223
	v_sub_f32_e32 v231, v231, v206
	v_sub_f32_e32 v230, v230, v206
	v_sub_f32_e32 v233, v221, v206
	v_sub_f32_e32 v232, v205, v206
	v_pk_mul_f32 v[232:233], v[206:207], v[232:233] op_sel:[1,0]
	v_pk_mul_f32 v[230:231], v[206:207], v[230:231] op_sel:[1,0]
	s_waitcnt vmcnt(0)
	v_lshlrev_b32_e32 v222, 16, v224
	v_and_b32_e32 v223, 0xffff0000, v224
	v_lshlrev_b32_e32 v224, 16, v225
	v_and_b32_e32 v225, 0xffff0000, v225
	v_pk_fma_f32 v[230:231], v[162:163], v[230:231], v[166:167]
	v_pk_fma_f32 v[232:233], v[160:161], v[232:233], v[164:165]
	v_pk_fma_f32 v[224:225], v[228:229], v[224:225], v[230:231]
	v_pk_fma_f32 v[222:223], v[226:227], v[222:223], v[232:233]
	global_store_dwordx4 v[208:209], v[222:225], off offset:64
	global_load_dwordx2 v[222:223], v[210:211], off offset:256
	s_nop 0
	global_load_dwordx2 v[224:225], v[212:213], off offset:256
	v_pk_mul_f32 v[226:227], v[30:31], v[206:207] op_sel_hi:[1,0]
	v_pk_mul_f32 v[228:229], v[28:29], v[206:207] op_sel_hi:[1,0]
	v_pk_fma_f32 v[226:227], v[130:131], s[26:27], v[226:227] op_sel_hi:[1,0,1] neg_lo:[0,0,1] neg_hi:[0,0,1]
	v_pk_fma_f32 v[228:229], v[128:129], s[26:27], v[228:229] op_sel_hi:[1,0,1] neg_lo:[0,0,1] neg_hi:[0,0,1]
	v_pk_fma_f32 v[226:227], v[206:207], v[226:227], v[26:27] op_sel:[1,0,0]
	v_pk_fma_f32 v[228:229], v[206:207], v[228:229], v[24:25] op_sel:[1,0,0]
	v_mul_f32_e32 v226, 0xbfb8aa3b, v226
	v_mul_f32_e32 v205, 0xbfb8aa3b, v228
	v_mul_f32_e32 v221, 0xbfb8aa3b, v229
	v_mul_f32_e32 v227, 0xbfb8aa3b, v227
	v_exp_f32_e32 v205, v205
	v_exp_f32_e32 v221, v221
	v_exp_f32_e32 v226, v226
	v_exp_f32_e32 v227, v227
	v_add_f32_e32 v205, 1.0, v205
	v_add_f32_e32 v221, 1.0, v221
	v_add_f32_e32 v228, 1.0, v226
	v_add_f32_e32 v229, 1.0, v227
	v_rcp_f32_e32 v226, v205
	v_rcp_f32_e32 v227, v221
	v_rcp_f32_e32 v228, v228
	v_rcp_f32_e32 v229, v229
	s_waitcnt vmcnt(1)
	v_lshlrev_b32_e32 v205, 16, v222
	v_and_b32_e32 v221, 0xffff0000, v222
	v_lshlrev_b32_e32 v230, 16, v223
	v_and_b32_e32 v231, 0xffff0000, v223
	v_sub_f32_e32 v231, v231, v206
	v_sub_f32_e32 v230, v230, v206
	v_sub_f32_e32 v233, v221, v206
	v_sub_f32_e32 v232, v205, v206
	v_pk_mul_f32 v[232:233], v[206:207], v[232:233] op_sel:[1,0]
	v_pk_mul_f32 v[230:231], v[206:207], v[230:231] op_sel:[1,0]
	s_waitcnt vmcnt(0)
	v_lshlrev_b32_e32 v222, 16, v224
	v_and_b32_e32 v223, 0xffff0000, v224
	v_lshlrev_b32_e32 v224, 16, v225
	v_and_b32_e32 v225, 0xffff0000, v225
	v_pk_fma_f32 v[230:231], v[18:19], v[230:231], v[22:23]
	v_pk_fma_f32 v[232:233], v[16:17], v[232:233], v[20:21]
	v_pk_fma_f32 v[224:225], v[228:229], v[224:225], v[230:231]
	v_pk_fma_f32 v[222:223], v[226:227], v[222:223], v[232:233]
	global_store_dwordx4 v[208:209], v[222:225], off offset:512
	global_load_dwordx2 v[222:223], v[210:211], off offset:288
	s_nop 0
	global_load_dwordx2 v[212:213], v[212:213], off offset:288
	v_pk_mul_f32 v[224:225], v[14:15], v[206:207] op_sel_hi:[1,0]
	v_pk_mul_f32 v[232:233], v[12:13], v[206:207] op_sel_hi:[1,0]
	v_pk_fma_f32 v[224:225], v[122:123], s[26:27], v[224:225] op_sel_hi:[1,0,1] neg_lo:[0,0,1] neg_hi:[0,0,1]
	v_pk_fma_f32 v[232:233], v[120:121], s[26:27], v[232:233] op_sel_hi:[1,0,1] neg_lo:[0,0,1] neg_hi:[0,0,1]
	v_pk_fma_f32 v[224:225], v[206:207], v[224:225], v[10:11] op_sel:[1,0,0]
	v_pk_fma_f32 v[232:233], v[206:207], v[232:233], v[8:9] op_sel:[1,0,0]
	v_mul_f32_e32 v224, 0xbfb8aa3b, v224
	v_mul_f32_e32 v205, 0xbfb8aa3b, v232
	v_mul_f32_e32 v221, 0xbfb8aa3b, v233
	v_mul_f32_e32 v225, 0xbfb8aa3b, v225
	v_exp_f32_e32 v205, v205
	v_exp_f32_e32 v221, v221
	v_exp_f32_e32 v224, v224
	v_exp_f32_e32 v225, v225
	v_add_f32_e32 v205, 1.0, v205
	v_add_f32_e32 v221, 1.0, v221
	v_add_f32_e32 v232, 1.0, v224
	v_add_f32_e32 v233, 1.0, v225
	v_or_b32_e32 v226, 32, v204
	v_rcp_f32_e32 v224, v205
	v_rcp_f32_e32 v225, v221
	v_rcp_f32_e32 v232, v232
	v_rcp_f32_e32 v233, v233
	v_ashrrev_i32_e32 v227, 31, v226
	v_lshlrev_b64 v[210:211], 12, v[226:227]
	v_lshl_add_u64 v[228:229], v[210:211], 0, v[202:203]
	v_lshlrev_b64 v[230:231], 1, v[228:229]
	v_lshl_add_u64 v[210:211], s[12:13], 0, v[230:231]
	s_waitcnt vmcnt(1)
	v_lshlrev_b32_e32 v205, 16, v222
	v_and_b32_e32 v221, 0xffff0000, v222
	v_lshlrev_b32_e32 v234, 16, v223
	v_and_b32_e32 v235, 0xffff0000, v223
	v_sub_f32_e32 v235, v235, v206
	v_sub_f32_e32 v234, v234, v206
	v_sub_f32_e32 v237, v221, v206
	v_sub_f32_e32 v236, v205, v206
	v_pk_mul_f32 v[236:237], v[206:207], v[236:237] op_sel:[1,0]
	v_pk_mul_f32 v[206:207], v[206:207], v[234:235] op_sel:[1,0]
	s_waitcnt vmcnt(0)
	v_lshlrev_b32_e32 v222, 16, v212
	v_and_b32_e32 v223, 0xffff0000, v212
	v_lshlrev_b32_e32 v212, 16, v213
	v_and_b32_e32 v213, 0xffff0000, v213
	v_pk_fma_f32 v[206:207], v[2:3], v[206:207], v[6:7]
	v_pk_fma_f32 v[234:235], v[0:1], v[236:237], v[4:5]
	s_nop 0
	v_pk_fma_f32 v[222:223], v[224:225], v[222:223], v[234:235]
	v_pk_fma_f32 v[224:225], v[232:233], v[212:213], v[206:207]
	global_store_dwordx4 v[208:209], v[222:225], off offset:576
	v_lshl_add_u64 v[206:207], v[226:227], 3, s[0:1]
	v_lshl_add_u64 v[212:213], s[18:19], 0, v[230:231]
	global_load_dwordx2 v[222:223], v[210:211], off
	global_load_dwordx2 v[224:225], v[212:213], off
	s_nop 0
	global_load_dwordx2 v[206:207], v[206:207], off
	v_lshl_add_u64 v[208:209], v[228:229], 2, s[14:15]
	s_waitcnt vmcnt(2)
	v_lshlrev_b32_e32 v205, 16, v222
	v_and_b32_e32 v221, 0xffff0000, v222
	v_lshlrev_b32_e32 v230, 16, v223
	v_and_b32_e32 v231, 0xffff0000, v223
	s_waitcnt vmcnt(0)
	v_pk_mul_f32 v[222:223], v[178:179], v[206:207] op_sel_hi:[1,0]
	v_pk_mul_f32 v[226:227], v[176:177], v[206:207] op_sel_hi:[1,0]
	v_pk_fma_f32 v[222:223], v[134:135], s[26:27], v[222:223] op_sel_hi:[1,0,1] neg_lo:[0,0,1] neg_hi:[0,0,1]
	v_pk_fma_f32 v[226:227], v[132:133], s[26:27], v[226:227] op_sel_hi:[1,0,1] neg_lo:[0,0,1] neg_hi:[0,0,1]
	v_pk_fma_f32 v[222:223], v[206:207], v[222:223], v[190:191] op_sel:[1,0,0]
	v_pk_fma_f32 v[226:227], v[206:207], v[226:227], v[188:189] op_sel:[1,0,0]
	v_sub_f32_e32 v233, v221, v206
	v_sub_f32_e32 v232, v205, v206
	v_mul_f32_e32 v205, 0xbfb8aa3b, v226
	v_mul_f32_e32 v221, 0xbfb8aa3b, v227
	v_mul_f32_e32 v222, 0xbfb8aa3b, v222
	v_mul_f32_e32 v223, 0xbfb8aa3b, v223
	v_exp_f32_e32 v205, v205
	v_exp_f32_e32 v221, v221
	v_exp_f32_e32 v222, v222
	v_exp_f32_e32 v223, v223
	v_add_f32_e32 v205, 1.0, v205
	v_add_f32_e32 v221, 1.0, v221
	v_add_f32_e32 v226, 1.0, v222
	v_add_f32_e32 v227, 1.0, v223
	v_rcp_f32_e32 v222, v205
	v_rcp_f32_e32 v223, v221
	v_rcp_f32_e32 v226, v226
	v_rcp_f32_e32 v227, v227
	v_sub_f32_e32 v231, v231, v206
	v_sub_f32_e32 v230, v230, v206
	v_pk_mul_f32 v[232:233], v[206:207], v[232:233] op_sel:[1,0]
	v_pk_mul_f32 v[230:231], v[206:207], v[230:231] op_sel:[1,0]
	v_lshlrev_b32_e32 v228, 16, v224
	v_and_b32_e32 v229, 0xffff0000, v224
	v_lshlrev_b32_e32 v224, 16, v225
	v_and_b32_e32 v225, 0xffff0000, v225
	v_pk_fma_f32 v[230:231], v[186:187], v[230:231], v[182:183]
	v_pk_fma_f32 v[232:233], v[184:185], v[232:233], v[180:181]
	v_pk_fma_f32 v[224:225], v[226:227], v[224:225], v[230:231]
	v_pk_fma_f32 v[222:223], v[222:223], v[228:229], v[232:233]
	global_store_dwordx4 v[208:209], v[222:225], off
	global_load_dwordx2 v[222:223], v[210:211], off offset:32
	s_nop 0
	global_load_dwordx2 v[224:225], v[212:213], off offset:32
	v_pk_mul_f32 v[226:227], v[174:175], v[206:207] op_sel_hi:[1,0]
	v_pk_mul_f32 v[228:229], v[172:173], v[206:207] op_sel_hi:[1,0]
	v_pk_fma_f32 v[226:227], v[126:127], s[26:27], v[226:227] op_sel_hi:[1,0,1] neg_lo:[0,0,1] neg_hi:[0,0,1]
	v_pk_fma_f32 v[228:229], v[124:125], s[26:27], v[228:229] op_sel_hi:[1,0,1] neg_lo:[0,0,1] neg_hi:[0,0,1]
	v_pk_fma_f32 v[226:227], v[206:207], v[226:227], v[170:171] op_sel:[1,0,0]
	v_pk_fma_f32 v[228:229], v[206:207], v[228:229], v[168:169] op_sel:[1,0,0]
	v_mul_f32_e32 v226, 0xbfb8aa3b, v226
	v_mul_f32_e32 v205, 0xbfb8aa3b, v228
	v_mul_f32_e32 v221, 0xbfb8aa3b, v229
	v_mul_f32_e32 v227, 0xbfb8aa3b, v227
	v_exp_f32_e32 v205, v205
	v_exp_f32_e32 v221, v221
	v_exp_f32_e32 v226, v226
	v_exp_f32_e32 v227, v227
	v_add_f32_e32 v205, 1.0, v205
	v_add_f32_e32 v221, 1.0, v221
	v_add_f32_e32 v228, 1.0, v226
	v_add_f32_e32 v229, 1.0, v227
	v_rcp_f32_e32 v226, v205
	v_rcp_f32_e32 v227, v221
	v_rcp_f32_e32 v228, v228
	v_rcp_f32_e32 v229, v229
	s_waitcnt vmcnt(1)
	v_lshlrev_b32_e32 v205, 16, v222
	v_and_b32_e32 v221, 0xffff0000, v222
	v_lshlrev_b32_e32 v230, 16, v223
	v_and_b32_e32 v231, 0xffff0000, v223
	v_sub_f32_e32 v231, v231, v206
	v_sub_f32_e32 v230, v230, v206
	v_sub_f32_e32 v233, v221, v206
	v_sub_f32_e32 v232, v205, v206
	v_pk_mul_f32 v[232:233], v[206:207], v[232:233] op_sel:[1,0]
	v_pk_mul_f32 v[230:231], v[206:207], v[230:231] op_sel:[1,0]
	s_waitcnt vmcnt(0)
	v_lshlrev_b32_e32 v222, 16, v224
	v_and_b32_e32 v223, 0xffff0000, v224
	v_lshlrev_b32_e32 v224, 16, v225
	v_and_b32_e32 v225, 0xffff0000, v225
	v_pk_fma_f32 v[230:231], v[162:163], v[230:231], v[166:167]
	v_pk_fma_f32 v[232:233], v[160:161], v[232:233], v[164:165]
	v_pk_fma_f32 v[224:225], v[228:229], v[224:225], v[230:231]
	v_pk_fma_f32 v[222:223], v[226:227], v[222:223], v[232:233]
	global_store_dwordx4 v[208:209], v[222:225], off offset:64
	global_load_dwordx2 v[222:223], v[210:211], off offset:256
	s_nop 0
	global_load_dwordx2 v[224:225], v[212:213], off offset:256
	v_pk_mul_f32 v[226:227], v[30:31], v[206:207] op_sel_hi:[1,0]
	v_pk_mul_f32 v[228:229], v[28:29], v[206:207] op_sel_hi:[1,0]
	v_pk_fma_f32 v[226:227], v[114:115], s[26:27], v[226:227] op_sel_hi:[1,0,1] neg_lo:[0,0,1] neg_hi:[0,0,1]
	v_pk_fma_f32 v[228:229], v[112:113], s[26:27], v[228:229] op_sel_hi:[1,0,1] neg_lo:[0,0,1] neg_hi:[0,0,1]
	v_pk_fma_f32 v[226:227], v[206:207], v[226:227], v[26:27] op_sel:[1,0,0]
	v_pk_fma_f32 v[228:229], v[206:207], v[228:229], v[24:25] op_sel:[1,0,0]
	v_mul_f32_e32 v226, 0xbfb8aa3b, v226
	v_mul_f32_e32 v205, 0xbfb8aa3b, v228
	v_mul_f32_e32 v221, 0xbfb8aa3b, v229
	v_mul_f32_e32 v227, 0xbfb8aa3b, v227
	v_exp_f32_e32 v205, v205
	v_exp_f32_e32 v221, v221
	v_exp_f32_e32 v226, v226
	v_exp_f32_e32 v227, v227
	v_add_f32_e32 v205, 1.0, v205
	v_add_f32_e32 v221, 1.0, v221
	v_add_f32_e32 v228, 1.0, v226
	v_add_f32_e32 v229, 1.0, v227
	v_rcp_f32_e32 v226, v205
	v_rcp_f32_e32 v227, v221
	v_rcp_f32_e32 v228, v228
	v_rcp_f32_e32 v229, v229
	s_waitcnt vmcnt(1)
	v_lshlrev_b32_e32 v205, 16, v222
	v_and_b32_e32 v221, 0xffff0000, v222
	v_lshlrev_b32_e32 v230, 16, v223
	v_and_b32_e32 v231, 0xffff0000, v223
	v_sub_f32_e32 v231, v231, v206
	v_sub_f32_e32 v230, v230, v206
	v_sub_f32_e32 v233, v221, v206
	v_sub_f32_e32 v232, v205, v206
	v_pk_mul_f32 v[232:233], v[206:207], v[232:233] op_sel:[1,0]
	v_pk_mul_f32 v[230:231], v[206:207], v[230:231] op_sel:[1,0]
	s_waitcnt vmcnt(0)
	v_lshlrev_b32_e32 v222, 16, v224
	v_and_b32_e32 v223, 0xffff0000, v224
	v_lshlrev_b32_e32 v224, 16, v225
	v_and_b32_e32 v225, 0xffff0000, v225
	v_pk_fma_f32 v[230:231], v[18:19], v[230:231], v[22:23]
	v_pk_fma_f32 v[232:233], v[16:17], v[232:233], v[20:21]
	v_pk_fma_f32 v[224:225], v[228:229], v[224:225], v[230:231]
	v_pk_fma_f32 v[222:223], v[226:227], v[222:223], v[232:233]
	global_store_dwordx4 v[208:209], v[222:225], off offset:512
	global_load_dwordx2 v[222:223], v[210:211], off offset:288
	s_nop 0
	global_load_dwordx2 v[212:213], v[212:213], off offset:288
	v_pk_mul_f32 v[224:225], v[14:15], v[206:207] op_sel_hi:[1,0]
	v_pk_mul_f32 v[232:233], v[12:13], v[206:207] op_sel_hi:[1,0]
	v_pk_fma_f32 v[224:225], v[106:107], s[26:27], v[224:225] op_sel_hi:[1,0,1] neg_lo:[0,0,1] neg_hi:[0,0,1]
	v_pk_fma_f32 v[232:233], v[104:105], s[26:27], v[232:233] op_sel_hi:[1,0,1] neg_lo:[0,0,1] neg_hi:[0,0,1]
	v_pk_fma_f32 v[224:225], v[206:207], v[224:225], v[10:11] op_sel:[1,0,0]
	v_pk_fma_f32 v[232:233], v[206:207], v[232:233], v[8:9] op_sel:[1,0,0]
	v_mul_f32_e32 v224, 0xbfb8aa3b, v224
	v_mul_f32_e32 v205, 0xbfb8aa3b, v232
	v_mul_f32_e32 v221, 0xbfb8aa3b, v233
	v_mul_f32_e32 v225, 0xbfb8aa3b, v225
	v_exp_f32_e32 v205, v205
	v_exp_f32_e32 v221, v221
	v_exp_f32_e32 v224, v224
	v_exp_f32_e32 v225, v225
	v_add_f32_e32 v205, 1.0, v205
	v_add_f32_e32 v221, 1.0, v221
	v_add_f32_e32 v232, 1.0, v224
	v_add_f32_e32 v233, 1.0, v225
	v_or_b32_e32 v226, 48, v204
	v_rcp_f32_e32 v224, v205
	v_rcp_f32_e32 v225, v221
	v_rcp_f32_e32 v232, v232
	v_rcp_f32_e32 v233, v233
	v_ashrrev_i32_e32 v227, 31, v226
	v_lshlrev_b64 v[210:211], 12, v[226:227]
	v_lshl_add_u64 v[228:229], v[210:211], 0, v[202:203]
	v_lshlrev_b64 v[230:231], 1, v[228:229]
	v_lshl_add_u64 v[210:211], s[12:13], 0, v[230:231]
	s_waitcnt vmcnt(1)
	v_lshlrev_b32_e32 v205, 16, v222
	v_and_b32_e32 v221, 0xffff0000, v222
	v_lshlrev_b32_e32 v234, 16, v223
	v_and_b32_e32 v235, 0xffff0000, v223
	v_sub_f32_e32 v235, v235, v206
	v_sub_f32_e32 v234, v234, v206
	v_sub_f32_e32 v237, v221, v206
	v_sub_f32_e32 v236, v205, v206
	v_pk_mul_f32 v[236:237], v[206:207], v[236:237] op_sel:[1,0]
	v_pk_mul_f32 v[206:207], v[206:207], v[234:235] op_sel:[1,0]
	s_waitcnt vmcnt(0)
	v_lshlrev_b32_e32 v222, 16, v212
	v_and_b32_e32 v223, 0xffff0000, v212
	v_lshlrev_b32_e32 v212, 16, v213
	v_and_b32_e32 v213, 0xffff0000, v213
	v_pk_fma_f32 v[206:207], v[2:3], v[206:207], v[6:7]
	v_pk_fma_f32 v[234:235], v[0:1], v[236:237], v[4:5]
	s_nop 0
	v_pk_fma_f32 v[222:223], v[224:225], v[222:223], v[234:235]
	v_pk_fma_f32 v[224:225], v[232:233], v[212:213], v[206:207]
	global_store_dwordx4 v[208:209], v[222:225], off offset:576
	v_lshl_add_u64 v[206:207], v[226:227], 3, s[0:1]
	v_lshl_add_u64 v[212:213], s[18:19], 0, v[230:231]
	global_load_dwordx2 v[222:223], v[210:211], off
	global_load_dwordx2 v[224:225], v[212:213], off
	s_nop 0
	global_load_dwordx2 v[206:207], v[206:207], off
	v_lshl_add_u64 v[208:209], v[228:229], 2, s[14:15]
	s_waitcnt vmcnt(2)
	v_lshlrev_b32_e32 v205, 16, v222
	v_and_b32_e32 v221, 0xffff0000, v222
	v_lshlrev_b32_e32 v230, 16, v223
	v_and_b32_e32 v231, 0xffff0000, v223
	s_waitcnt vmcnt(0)
	v_pk_mul_f32 v[222:223], v[178:179], v[206:207] op_sel_hi:[1,0]
	v_pk_mul_f32 v[226:227], v[176:177], v[206:207] op_sel_hi:[1,0]
	v_pk_fma_f32 v[222:223], v[118:119], s[26:27], v[222:223] op_sel_hi:[1,0,1] neg_lo:[0,0,1] neg_hi:[0,0,1]
	v_pk_fma_f32 v[226:227], v[116:117], s[26:27], v[226:227] op_sel_hi:[1,0,1] neg_lo:[0,0,1] neg_hi:[0,0,1]
	v_pk_fma_f32 v[222:223], v[206:207], v[222:223], v[190:191] op_sel:[1,0,0]
	v_pk_fma_f32 v[226:227], v[206:207], v[226:227], v[188:189] op_sel:[1,0,0]
	v_sub_f32_e32 v233, v221, v206
	v_sub_f32_e32 v232, v205, v206
	v_mul_f32_e32 v205, 0xbfb8aa3b, v226
	v_mul_f32_e32 v221, 0xbfb8aa3b, v227
	v_mul_f32_e32 v222, 0xbfb8aa3b, v222
	v_mul_f32_e32 v223, 0xbfb8aa3b, v223
	v_exp_f32_e32 v205, v205
	v_exp_f32_e32 v221, v221
	v_exp_f32_e32 v222, v222
	v_exp_f32_e32 v223, v223
	v_add_f32_e32 v205, 1.0, v205
	v_add_f32_e32 v221, 1.0, v221
	v_add_f32_e32 v226, 1.0, v222
	v_add_f32_e32 v227, 1.0, v223
	v_rcp_f32_e32 v222, v205
	v_rcp_f32_e32 v223, v221
	v_rcp_f32_e32 v226, v226
	v_rcp_f32_e32 v227, v227
	v_sub_f32_e32 v231, v231, v206
	v_sub_f32_e32 v230, v230, v206
	v_pk_mul_f32 v[232:233], v[206:207], v[232:233] op_sel:[1,0]
	v_pk_mul_f32 v[230:231], v[206:207], v[230:231] op_sel:[1,0]
	v_lshlrev_b32_e32 v228, 16, v224
	v_and_b32_e32 v229, 0xffff0000, v224
	v_lshlrev_b32_e32 v224, 16, v225
	v_and_b32_e32 v225, 0xffff0000, v225
	v_pk_fma_f32 v[230:231], v[186:187], v[230:231], v[182:183]
	v_pk_fma_f32 v[232:233], v[184:185], v[232:233], v[180:181]
	v_pk_fma_f32 v[224:225], v[226:227], v[224:225], v[230:231]
	v_pk_fma_f32 v[222:223], v[222:223], v[228:229], v[232:233]
	global_store_dwordx4 v[208:209], v[222:225], off
	global_load_dwordx2 v[222:223], v[210:211], off offset:32
	s_nop 0
	global_load_dwordx2 v[224:225], v[212:213], off offset:32
	v_pk_mul_f32 v[226:227], v[174:175], v[206:207] op_sel_hi:[1,0]
	v_pk_mul_f32 v[228:229], v[172:173], v[206:207] op_sel_hi:[1,0]
	v_pk_fma_f32 v[226:227], v[110:111], s[26:27], v[226:227] op_sel_hi:[1,0,1] neg_lo:[0,0,1] neg_hi:[0,0,1]
	v_pk_fma_f32 v[228:229], v[108:109], s[26:27], v[228:229] op_sel_hi:[1,0,1] neg_lo:[0,0,1] neg_hi:[0,0,1]
	v_pk_fma_f32 v[226:227], v[206:207], v[226:227], v[170:171] op_sel:[1,0,0]
	v_pk_fma_f32 v[228:229], v[206:207], v[228:229], v[168:169] op_sel:[1,0,0]
	v_mul_f32_e32 v226, 0xbfb8aa3b, v226
	v_mul_f32_e32 v205, 0xbfb8aa3b, v228
	v_mul_f32_e32 v221, 0xbfb8aa3b, v229
	v_mul_f32_e32 v227, 0xbfb8aa3b, v227
	v_exp_f32_e32 v205, v205
	v_exp_f32_e32 v221, v221
	v_exp_f32_e32 v226, v226
	v_exp_f32_e32 v227, v227
	v_add_f32_e32 v205, 1.0, v205
	v_add_f32_e32 v221, 1.0, v221
	v_add_f32_e32 v228, 1.0, v226
	v_add_f32_e32 v229, 1.0, v227
	v_rcp_f32_e32 v226, v205
	v_rcp_f32_e32 v227, v221
	v_rcp_f32_e32 v228, v228
	v_rcp_f32_e32 v229, v229
	s_waitcnt vmcnt(1)
	v_lshlrev_b32_e32 v205, 16, v222
	v_and_b32_e32 v221, 0xffff0000, v222
	v_lshlrev_b32_e32 v230, 16, v223
	v_and_b32_e32 v231, 0xffff0000, v223
	v_sub_f32_e32 v231, v231, v206
	v_sub_f32_e32 v230, v230, v206
	v_sub_f32_e32 v233, v221, v206
	v_sub_f32_e32 v232, v205, v206
	v_pk_mul_f32 v[232:233], v[206:207], v[232:233] op_sel:[1,0]
	v_pk_mul_f32 v[230:231], v[206:207], v[230:231] op_sel:[1,0]
	s_waitcnt vmcnt(0)
	v_lshlrev_b32_e32 v222, 16, v224
	v_and_b32_e32 v223, 0xffff0000, v224
	v_lshlrev_b32_e32 v224, 16, v225
	v_and_b32_e32 v225, 0xffff0000, v225
	v_pk_fma_f32 v[230:231], v[162:163], v[230:231], v[166:167]
	v_pk_fma_f32 v[232:233], v[160:161], v[232:233], v[164:165]
	v_pk_fma_f32 v[224:225], v[228:229], v[224:225], v[230:231]
	v_pk_fma_f32 v[222:223], v[226:227], v[222:223], v[232:233]
	global_store_dwordx4 v[208:209], v[222:225], off offset:64
	global_load_dwordx2 v[222:223], v[210:211], off offset:256
	s_nop 0
	global_load_dwordx2 v[224:225], v[212:213], off offset:256
	v_pk_mul_f32 v[226:227], v[30:31], v[206:207] op_sel_hi:[1,0]
	v_pk_mul_f32 v[228:229], v[28:29], v[206:207] op_sel_hi:[1,0]
	v_pk_fma_f32 v[226:227], v[102:103], s[26:27], v[226:227] op_sel_hi:[1,0,1] neg_lo:[0,0,1] neg_hi:[0,0,1]
	v_pk_fma_f32 v[228:229], v[100:101], s[26:27], v[228:229] op_sel_hi:[1,0,1] neg_lo:[0,0,1] neg_hi:[0,0,1]
	v_pk_fma_f32 v[226:227], v[206:207], v[226:227], v[26:27] op_sel:[1,0,0]
	v_pk_fma_f32 v[228:229], v[206:207], v[228:229], v[24:25] op_sel:[1,0,0]
	v_mul_f32_e32 v226, 0xbfb8aa3b, v226
	v_mul_f32_e32 v205, 0xbfb8aa3b, v228
	v_mul_f32_e32 v221, 0xbfb8aa3b, v229
	v_mul_f32_e32 v227, 0xbfb8aa3b, v227
	v_exp_f32_e32 v205, v205
	v_exp_f32_e32 v221, v221
	v_exp_f32_e32 v226, v226
	v_exp_f32_e32 v227, v227
	v_add_f32_e32 v205, 1.0, v205
	v_add_f32_e32 v221, 1.0, v221
	v_add_f32_e32 v228, 1.0, v226
	v_add_f32_e32 v229, 1.0, v227
	v_rcp_f32_e32 v226, v205
	v_rcp_f32_e32 v227, v221
	v_rcp_f32_e32 v228, v228
	v_rcp_f32_e32 v229, v229
	s_waitcnt vmcnt(1)
	v_lshlrev_b32_e32 v205, 16, v222
	v_and_b32_e32 v221, 0xffff0000, v222
	v_lshlrev_b32_e32 v230, 16, v223
	v_and_b32_e32 v231, 0xffff0000, v223
	v_sub_f32_e32 v231, v231, v206
	v_sub_f32_e32 v230, v230, v206
	v_sub_f32_e32 v233, v221, v206
	v_sub_f32_e32 v232, v205, v206
	v_pk_mul_f32 v[232:233], v[206:207], v[232:233] op_sel:[1,0]
	v_pk_mul_f32 v[230:231], v[206:207], v[230:231] op_sel:[1,0]
	s_waitcnt vmcnt(0)
	v_lshlrev_b32_e32 v222, 16, v224
	v_and_b32_e32 v223, 0xffff0000, v224
	v_lshlrev_b32_e32 v224, 16, v225
	v_and_b32_e32 v225, 0xffff0000, v225
	v_pk_fma_f32 v[230:231], v[18:19], v[230:231], v[22:23]
	v_pk_fma_f32 v[232:233], v[16:17], v[232:233], v[20:21]
	v_pk_fma_f32 v[224:225], v[228:229], v[224:225], v[230:231]
	v_pk_fma_f32 v[222:223], v[226:227], v[222:223], v[232:233]
	global_store_dwordx4 v[208:209], v[222:225], off offset:512
	global_load_dwordx2 v[222:223], v[210:211], off offset:288
	s_nop 0
	global_load_dwordx2 v[212:213], v[212:213], off offset:288
	v_pk_mul_f32 v[224:225], v[14:15], v[206:207] op_sel_hi:[1,0]
	v_pk_mul_f32 v[232:233], v[12:13], v[206:207] op_sel_hi:[1,0]
	v_pk_fma_f32 v[224:225], v[98:99], s[26:27], v[224:225] op_sel_hi:[1,0,1] neg_lo:[0,0,1] neg_hi:[0,0,1]
	v_pk_fma_f32 v[232:233], v[96:97], s[26:27], v[232:233] op_sel_hi:[1,0,1] neg_lo:[0,0,1] neg_hi:[0,0,1]
	v_pk_fma_f32 v[224:225], v[206:207], v[224:225], v[10:11] op_sel:[1,0,0]
	v_pk_fma_f32 v[232:233], v[206:207], v[232:233], v[8:9] op_sel:[1,0,0]
	v_mul_f32_e32 v224, 0xbfb8aa3b, v224
	v_mul_f32_e32 v205, 0xbfb8aa3b, v232
	v_mul_f32_e32 v221, 0xbfb8aa3b, v233
	v_mul_f32_e32 v225, 0xbfb8aa3b, v225
	v_exp_f32_e32 v205, v205
	v_exp_f32_e32 v221, v221
	v_exp_f32_e32 v224, v224
	v_exp_f32_e32 v225, v225
	v_add_f32_e32 v205, 1.0, v205
	v_add_f32_e32 v221, 1.0, v221
	v_add_f32_e32 v232, 1.0, v224
	v_add_f32_e32 v233, 1.0, v225
	v_add_u32_e32 v226, 0x80, v204
	v_rcp_f32_e32 v224, v205
	v_rcp_f32_e32 v225, v221
	v_rcp_f32_e32 v232, v232
	v_rcp_f32_e32 v233, v233
	v_ashrrev_i32_e32 v227, 31, v226
	v_lshlrev_b64 v[210:211], 12, v[226:227]
	v_lshl_add_u64 v[228:229], v[210:211], 0, v[202:203]
	v_lshlrev_b64 v[230:231], 1, v[228:229]
	v_lshl_add_u64 v[210:211], s[12:13], 0, v[230:231]
	s_waitcnt vmcnt(1)
	v_lshlrev_b32_e32 v205, 16, v222
	v_and_b32_e32 v221, 0xffff0000, v222
	v_lshlrev_b32_e32 v234, 16, v223
	v_and_b32_e32 v235, 0xffff0000, v223
	v_sub_f32_e32 v235, v235, v206
	v_sub_f32_e32 v234, v234, v206
	v_sub_f32_e32 v237, v221, v206
	v_sub_f32_e32 v236, v205, v206
	v_pk_mul_f32 v[236:237], v[206:207], v[236:237] op_sel:[1,0]
	v_pk_mul_f32 v[206:207], v[206:207], v[234:235] op_sel:[1,0]
	s_waitcnt vmcnt(0)
	v_lshlrev_b32_e32 v222, 16, v212
	v_and_b32_e32 v223, 0xffff0000, v212
	v_lshlrev_b32_e32 v212, 16, v213
	v_and_b32_e32 v213, 0xffff0000, v213
	v_pk_fma_f32 v[206:207], v[2:3], v[206:207], v[6:7]
	v_pk_fma_f32 v[234:235], v[0:1], v[236:237], v[4:5]
	s_nop 0
	v_pk_fma_f32 v[222:223], v[224:225], v[222:223], v[234:235]
	v_pk_fma_f32 v[224:225], v[232:233], v[212:213], v[206:207]
	global_store_dwordx4 v[208:209], v[222:225], off offset:576
	v_lshl_add_u64 v[206:207], v[226:227], 3, s[0:1]
	v_lshl_add_u64 v[212:213], s[18:19], 0, v[230:231]
	global_load_dwordx2 v[222:223], v[210:211], off
	global_load_dwordx2 v[224:225], v[212:213], off
	s_nop 0
	global_load_dwordx2 v[206:207], v[206:207], off
	v_lshl_add_u64 v[208:209], v[228:229], 2, s[14:15]
	s_waitcnt vmcnt(2)
	v_lshlrev_b32_e32 v205, 16, v222
	v_and_b32_e32 v221, 0xffff0000, v222
	v_lshlrev_b32_e32 v230, 16, v223
	v_and_b32_e32 v231, 0xffff0000, v223
	s_waitcnt vmcnt(0)
	v_pk_mul_f32 v[222:223], v[178:179], v[206:207] op_sel_hi:[1,0]
	v_pk_mul_f32 v[226:227], v[176:177], v[206:207] op_sel_hi:[1,0]
	v_pk_fma_f32 v[222:223], v[94:95], s[26:27], v[222:223] op_sel_hi:[1,0,1] neg_lo:[0,0,1] neg_hi:[0,0,1]
	v_pk_fma_f32 v[226:227], v[92:93], s[26:27], v[226:227] op_sel_hi:[1,0,1] neg_lo:[0,0,1] neg_hi:[0,0,1]
	v_pk_fma_f32 v[222:223], v[206:207], v[222:223], v[190:191] op_sel:[1,0,0]
	v_pk_fma_f32 v[226:227], v[206:207], v[226:227], v[188:189] op_sel:[1,0,0]
	v_sub_f32_e32 v233, v221, v206
	v_sub_f32_e32 v232, v205, v206
	v_mul_f32_e32 v205, 0xbfb8aa3b, v226
	v_mul_f32_e32 v221, 0xbfb8aa3b, v227
	v_mul_f32_e32 v222, 0xbfb8aa3b, v222
	v_mul_f32_e32 v223, 0xbfb8aa3b, v223
	v_exp_f32_e32 v205, v205
	v_exp_f32_e32 v221, v221
	v_exp_f32_e32 v222, v222
	v_exp_f32_e32 v223, v223
	v_add_f32_e32 v205, 1.0, v205
	v_add_f32_e32 v221, 1.0, v221
	v_add_f32_e32 v226, 1.0, v222
	v_add_f32_e32 v227, 1.0, v223
	v_rcp_f32_e32 v222, v205
	v_rcp_f32_e32 v223, v221
	v_rcp_f32_e32 v226, v226
	v_rcp_f32_e32 v227, v227
	v_sub_f32_e32 v231, v231, v206
	v_sub_f32_e32 v230, v230, v206
	v_pk_mul_f32 v[232:233], v[206:207], v[232:233] op_sel:[1,0]
	v_pk_mul_f32 v[230:231], v[206:207], v[230:231] op_sel:[1,0]
	v_lshlrev_b32_e32 v228, 16, v224
	v_and_b32_e32 v229, 0xffff0000, v224
	v_lshlrev_b32_e32 v224, 16, v225
	v_and_b32_e32 v225, 0xffff0000, v225
	v_pk_fma_f32 v[230:231], v[186:187], v[230:231], v[182:183]
	v_pk_fma_f32 v[232:233], v[184:185], v[232:233], v[180:181]
	v_pk_fma_f32 v[224:225], v[226:227], v[224:225], v[230:231]
	v_pk_fma_f32 v[222:223], v[222:223], v[228:229], v[232:233]
	global_store_dwordx4 v[208:209], v[222:225], off
	global_load_dwordx2 v[222:223], v[210:211], off offset:32
	s_nop 0
	global_load_dwordx2 v[224:225], v[212:213], off offset:32
	v_pk_mul_f32 v[226:227], v[174:175], v[206:207] op_sel_hi:[1,0]
	v_pk_mul_f32 v[228:229], v[172:173], v[206:207] op_sel_hi:[1,0]
	v_pk_fma_f32 v[226:227], v[90:91], s[26:27], v[226:227] op_sel_hi:[1,0,1] neg_lo:[0,0,1] neg_hi:[0,0,1]
	v_pk_fma_f32 v[228:229], v[88:89], s[26:27], v[228:229] op_sel_hi:[1,0,1] neg_lo:[0,0,1] neg_hi:[0,0,1]
	v_pk_fma_f32 v[226:227], v[206:207], v[226:227], v[170:171] op_sel:[1,0,0]
	v_pk_fma_f32 v[228:229], v[206:207], v[228:229], v[168:169] op_sel:[1,0,0]
	v_mul_f32_e32 v226, 0xbfb8aa3b, v226
	v_mul_f32_e32 v205, 0xbfb8aa3b, v228
	v_mul_f32_e32 v221, 0xbfb8aa3b, v229
	v_mul_f32_e32 v227, 0xbfb8aa3b, v227
	v_exp_f32_e32 v205, v205
	v_exp_f32_e32 v221, v221
	v_exp_f32_e32 v226, v226
	v_exp_f32_e32 v227, v227
	v_add_f32_e32 v205, 1.0, v205
	v_add_f32_e32 v221, 1.0, v221
	v_add_f32_e32 v228, 1.0, v226
	v_add_f32_e32 v229, 1.0, v227
	v_rcp_f32_e32 v226, v205
	v_rcp_f32_e32 v227, v221
	v_rcp_f32_e32 v228, v228
	v_rcp_f32_e32 v229, v229
	s_waitcnt vmcnt(1)
	v_lshlrev_b32_e32 v205, 16, v222
	v_and_b32_e32 v221, 0xffff0000, v222
	v_lshlrev_b32_e32 v230, 16, v223
	v_and_b32_e32 v231, 0xffff0000, v223
	v_sub_f32_e32 v231, v231, v206
	v_sub_f32_e32 v230, v230, v206
	v_sub_f32_e32 v233, v221, v206
	v_sub_f32_e32 v232, v205, v206
	v_pk_mul_f32 v[232:233], v[206:207], v[232:233] op_sel:[1,0]
	v_pk_mul_f32 v[230:231], v[206:207], v[230:231] op_sel:[1,0]
	s_waitcnt vmcnt(0)
	v_lshlrev_b32_e32 v222, 16, v224
	v_and_b32_e32 v223, 0xffff0000, v224
	v_lshlrev_b32_e32 v224, 16, v225
	v_and_b32_e32 v225, 0xffff0000, v225
	v_pk_fma_f32 v[230:231], v[162:163], v[230:231], v[166:167]
	v_pk_fma_f32 v[232:233], v[160:161], v[232:233], v[164:165]
	v_pk_fma_f32 v[224:225], v[228:229], v[224:225], v[230:231]
	v_pk_fma_f32 v[222:223], v[226:227], v[222:223], v[232:233]
	global_store_dwordx4 v[208:209], v[222:225], off offset:64
	global_load_dwordx2 v[222:223], v[210:211], off offset:256
	s_nop 0
	global_load_dwordx2 v[224:225], v[212:213], off offset:256
	v_pk_mul_f32 v[226:227], v[30:31], v[206:207] op_sel_hi:[1,0]
	v_pk_mul_f32 v[228:229], v[28:29], v[206:207] op_sel_hi:[1,0]
	v_pk_fma_f32 v[226:227], v[82:83], s[26:27], v[226:227] op_sel_hi:[1,0,1] neg_lo:[0,0,1] neg_hi:[0,0,1]
	v_pk_fma_f32 v[228:229], v[80:81], s[26:27], v[228:229] op_sel_hi:[1,0,1] neg_lo:[0,0,1] neg_hi:[0,0,1]
	v_pk_fma_f32 v[226:227], v[206:207], v[226:227], v[26:27] op_sel:[1,0,0]
	v_pk_fma_f32 v[228:229], v[206:207], v[228:229], v[24:25] op_sel:[1,0,0]
	v_mul_f32_e32 v226, 0xbfb8aa3b, v226
	v_mul_f32_e32 v205, 0xbfb8aa3b, v228
	v_mul_f32_e32 v221, 0xbfb8aa3b, v229
	v_mul_f32_e32 v227, 0xbfb8aa3b, v227
	v_exp_f32_e32 v205, v205
	v_exp_f32_e32 v221, v221
	v_exp_f32_e32 v226, v226
	v_exp_f32_e32 v227, v227
	v_add_f32_e32 v205, 1.0, v205
	v_add_f32_e32 v221, 1.0, v221
	v_add_f32_e32 v228, 1.0, v226
	v_add_f32_e32 v229, 1.0, v227
	v_rcp_f32_e32 v226, v205
	v_rcp_f32_e32 v227, v221
	v_rcp_f32_e32 v228, v228
	v_rcp_f32_e32 v229, v229
	s_waitcnt vmcnt(1)
	v_lshlrev_b32_e32 v205, 16, v222
	v_and_b32_e32 v221, 0xffff0000, v222
	v_lshlrev_b32_e32 v230, 16, v223
	v_and_b32_e32 v231, 0xffff0000, v223
	v_sub_f32_e32 v231, v231, v206
	v_sub_f32_e32 v230, v230, v206
	v_sub_f32_e32 v233, v221, v206
	v_sub_f32_e32 v232, v205, v206
	v_pk_mul_f32 v[232:233], v[206:207], v[232:233] op_sel:[1,0]
	v_pk_mul_f32 v[230:231], v[206:207], v[230:231] op_sel:[1,0]
	s_waitcnt vmcnt(0)
	v_lshlrev_b32_e32 v222, 16, v224
	v_and_b32_e32 v223, 0xffff0000, v224
	v_lshlrev_b32_e32 v224, 16, v225
	v_and_b32_e32 v225, 0xffff0000, v225
	v_pk_fma_f32 v[230:231], v[18:19], v[230:231], v[22:23]
	v_pk_fma_f32 v[232:233], v[16:17], v[232:233], v[20:21]
	v_pk_fma_f32 v[224:225], v[228:229], v[224:225], v[230:231]
	v_pk_fma_f32 v[222:223], v[226:227], v[222:223], v[232:233]
	global_store_dwordx4 v[208:209], v[222:225], off offset:512
	global_load_dwordx2 v[222:223], v[210:211], off offset:288
	s_nop 0
	global_load_dwordx2 v[212:213], v[212:213], off offset:288
	v_pk_mul_f32 v[224:225], v[14:15], v[206:207] op_sel_hi:[1,0]
	v_pk_mul_f32 v[232:233], v[12:13], v[206:207] op_sel_hi:[1,0]
	v_pk_fma_f32 v[224:225], v[78:79], s[26:27], v[224:225] op_sel_hi:[1,0,1] neg_lo:[0,0,1] neg_hi:[0,0,1]
	v_pk_fma_f32 v[232:233], v[76:77], s[26:27], v[232:233] op_sel_hi:[1,0,1] neg_lo:[0,0,1] neg_hi:[0,0,1]
	v_pk_fma_f32 v[224:225], v[206:207], v[224:225], v[10:11] op_sel:[1,0,0]
	v_pk_fma_f32 v[232:233], v[206:207], v[232:233], v[8:9] op_sel:[1,0,0]
	v_mul_f32_e32 v224, 0xbfb8aa3b, v224
	v_mul_f32_e32 v205, 0xbfb8aa3b, v232
	v_mul_f32_e32 v221, 0xbfb8aa3b, v233
	v_mul_f32_e32 v225, 0xbfb8aa3b, v225
	v_exp_f32_e32 v205, v205
	v_exp_f32_e32 v221, v221
	v_exp_f32_e32 v224, v224
	v_exp_f32_e32 v225, v225
	v_add_f32_e32 v205, 1.0, v205
	v_add_f32_e32 v221, 1.0, v221
	v_add_f32_e32 v232, 1.0, v224
	v_add_f32_e32 v233, 1.0, v225
	v_add_u32_e32 v226, 0x90, v204
	v_rcp_f32_e32 v224, v205
	v_rcp_f32_e32 v225, v221
	v_rcp_f32_e32 v232, v232
	v_rcp_f32_e32 v233, v233
	v_ashrrev_i32_e32 v227, 31, v226
	v_lshlrev_b64 v[210:211], 12, v[226:227]
	v_lshl_add_u64 v[228:229], v[210:211], 0, v[202:203]
	v_lshlrev_b64 v[230:231], 1, v[228:229]
	v_lshl_add_u64 v[210:211], s[12:13], 0, v[230:231]
	s_waitcnt vmcnt(1)
	v_lshlrev_b32_e32 v205, 16, v222
	v_and_b32_e32 v221, 0xffff0000, v222
	v_lshlrev_b32_e32 v234, 16, v223
	v_and_b32_e32 v235, 0xffff0000, v223
	v_sub_f32_e32 v235, v235, v206
	v_sub_f32_e32 v234, v234, v206
	v_sub_f32_e32 v237, v221, v206
	v_sub_f32_e32 v236, v205, v206
	v_pk_mul_f32 v[236:237], v[206:207], v[236:237] op_sel:[1,0]
	v_pk_mul_f32 v[206:207], v[206:207], v[234:235] op_sel:[1,0]
	s_waitcnt vmcnt(0)
	v_lshlrev_b32_e32 v222, 16, v212
	v_and_b32_e32 v223, 0xffff0000, v212
	v_lshlrev_b32_e32 v212, 16, v213
	v_and_b32_e32 v213, 0xffff0000, v213
	v_pk_fma_f32 v[206:207], v[2:3], v[206:207], v[6:7]
	v_pk_fma_f32 v[234:235], v[0:1], v[236:237], v[4:5]
	s_nop 0
	v_pk_fma_f32 v[222:223], v[224:225], v[222:223], v[234:235]
	v_pk_fma_f32 v[224:225], v[232:233], v[212:213], v[206:207]
	global_store_dwordx4 v[208:209], v[222:225], off offset:576
	v_lshl_add_u64 v[206:207], v[226:227], 3, s[0:1]
	v_lshl_add_u64 v[212:213], s[18:19], 0, v[230:231]
	global_load_dwordx2 v[222:223], v[210:211], off
	global_load_dwordx2 v[224:225], v[212:213], off
	s_nop 0
	global_load_dwordx2 v[206:207], v[206:207], off
	v_lshl_add_u64 v[208:209], v[228:229], 2, s[14:15]
	s_waitcnt vmcnt(2)
	v_lshlrev_b32_e32 v205, 16, v222
	v_and_b32_e32 v221, 0xffff0000, v222
	v_lshlrev_b32_e32 v230, 16, v223
	v_and_b32_e32 v231, 0xffff0000, v223
	s_waitcnt vmcnt(0)
	v_pk_mul_f32 v[222:223], v[178:179], v[206:207] op_sel_hi:[1,0]
	v_pk_mul_f32 v[226:227], v[176:177], v[206:207] op_sel_hi:[1,0]
	v_pk_fma_f32 v[222:223], v[86:87], s[26:27], v[222:223] op_sel_hi:[1,0,1] neg_lo:[0,0,1] neg_hi:[0,0,1]
	v_pk_fma_f32 v[226:227], v[84:85], s[26:27], v[226:227] op_sel_hi:[1,0,1] neg_lo:[0,0,1] neg_hi:[0,0,1]
	v_pk_fma_f32 v[222:223], v[206:207], v[222:223], v[190:191] op_sel:[1,0,0]
	v_pk_fma_f32 v[226:227], v[206:207], v[226:227], v[188:189] op_sel:[1,0,0]
	v_sub_f32_e32 v233, v221, v206
	v_sub_f32_e32 v232, v205, v206
	v_mul_f32_e32 v205, 0xbfb8aa3b, v226
	v_mul_f32_e32 v221, 0xbfb8aa3b, v227
	v_mul_f32_e32 v222, 0xbfb8aa3b, v222
	v_mul_f32_e32 v223, 0xbfb8aa3b, v223
	v_exp_f32_e32 v205, v205
	v_exp_f32_e32 v221, v221
	v_exp_f32_e32 v222, v222
	v_exp_f32_e32 v223, v223
	v_add_f32_e32 v205, 1.0, v205
	v_add_f32_e32 v221, 1.0, v221
	v_add_f32_e32 v226, 1.0, v222
	v_add_f32_e32 v227, 1.0, v223
	v_rcp_f32_e32 v222, v205
	v_rcp_f32_e32 v223, v221
	v_rcp_f32_e32 v226, v226
	v_rcp_f32_e32 v227, v227
	v_sub_f32_e32 v231, v231, v206
	v_sub_f32_e32 v230, v230, v206
	v_pk_mul_f32 v[232:233], v[206:207], v[232:233] op_sel:[1,0]
	v_pk_mul_f32 v[230:231], v[206:207], v[230:231] op_sel:[1,0]
	v_lshlrev_b32_e32 v228, 16, v224
	v_and_b32_e32 v229, 0xffff0000, v224
	v_lshlrev_b32_e32 v224, 16, v225
	v_and_b32_e32 v225, 0xffff0000, v225
	v_pk_fma_f32 v[230:231], v[186:187], v[230:231], v[182:183]
	v_pk_fma_f32 v[232:233], v[184:185], v[232:233], v[180:181]
	v_pk_fma_f32 v[224:225], v[226:227], v[224:225], v[230:231]
	v_pk_fma_f32 v[222:223], v[222:223], v[228:229], v[232:233]
	global_store_dwordx4 v[208:209], v[222:225], off
	global_load_dwordx2 v[222:223], v[210:211], off offset:32
	s_nop 0
	global_load_dwordx2 v[224:225], v[212:213], off offset:32
	v_pk_mul_f32 v[226:227], v[174:175], v[206:207] op_sel_hi:[1,0]
	v_pk_mul_f32 v[228:229], v[172:173], v[206:207] op_sel_hi:[1,0]
	v_pk_fma_f32 v[226:227], v[74:75], s[26:27], v[226:227] op_sel_hi:[1,0,1] neg_lo:[0,0,1] neg_hi:[0,0,1]
	v_pk_fma_f32 v[228:229], v[72:73], s[26:27], v[228:229] op_sel_hi:[1,0,1] neg_lo:[0,0,1] neg_hi:[0,0,1]
	v_pk_fma_f32 v[226:227], v[206:207], v[226:227], v[170:171] op_sel:[1,0,0]
	v_pk_fma_f32 v[228:229], v[206:207], v[228:229], v[168:169] op_sel:[1,0,0]
	v_mul_f32_e32 v226, 0xbfb8aa3b, v226
	v_mul_f32_e32 v205, 0xbfb8aa3b, v228
	v_mul_f32_e32 v221, 0xbfb8aa3b, v229
	v_mul_f32_e32 v227, 0xbfb8aa3b, v227
	v_exp_f32_e32 v205, v205
	v_exp_f32_e32 v221, v221
	v_exp_f32_e32 v226, v226
	v_exp_f32_e32 v227, v227
	v_add_f32_e32 v205, 1.0, v205
	v_add_f32_e32 v221, 1.0, v221
	v_add_f32_e32 v228, 1.0, v226
	v_add_f32_e32 v229, 1.0, v227
	v_rcp_f32_e32 v226, v205
	v_rcp_f32_e32 v227, v221
	v_rcp_f32_e32 v228, v228
	v_rcp_f32_e32 v229, v229
	s_waitcnt vmcnt(1)
	v_lshlrev_b32_e32 v205, 16, v222
	v_and_b32_e32 v221, 0xffff0000, v222
	v_lshlrev_b32_e32 v230, 16, v223
	v_and_b32_e32 v231, 0xffff0000, v223
	v_sub_f32_e32 v231, v231, v206
	v_sub_f32_e32 v230, v230, v206
	v_sub_f32_e32 v233, v221, v206
	v_sub_f32_e32 v232, v205, v206
	v_pk_mul_f32 v[232:233], v[206:207], v[232:233] op_sel:[1,0]
	v_pk_mul_f32 v[230:231], v[206:207], v[230:231] op_sel:[1,0]
	s_waitcnt vmcnt(0)
	v_lshlrev_b32_e32 v222, 16, v224
	v_and_b32_e32 v223, 0xffff0000, v224
	v_lshlrev_b32_e32 v224, 16, v225
	v_and_b32_e32 v225, 0xffff0000, v225
	v_pk_fma_f32 v[230:231], v[162:163], v[230:231], v[166:167]
	v_pk_fma_f32 v[232:233], v[160:161], v[232:233], v[164:165]
	v_pk_fma_f32 v[224:225], v[228:229], v[224:225], v[230:231]
	v_pk_fma_f32 v[222:223], v[226:227], v[222:223], v[232:233]
	global_store_dwordx4 v[208:209], v[222:225], off offset:64
	global_load_dwordx2 v[222:223], v[210:211], off offset:256
	s_nop 0
	global_load_dwordx2 v[224:225], v[212:213], off offset:256
	v_pk_mul_f32 v[226:227], v[30:31], v[206:207] op_sel_hi:[1,0]
	v_pk_mul_f32 v[228:229], v[28:29], v[206:207] op_sel_hi:[1,0]
	v_pk_fma_f32 v[226:227], v[66:67], s[26:27], v[226:227] op_sel_hi:[1,0,1] neg_lo:[0,0,1] neg_hi:[0,0,1]
	v_pk_fma_f32 v[228:229], v[64:65], s[26:27], v[228:229] op_sel_hi:[1,0,1] neg_lo:[0,0,1] neg_hi:[0,0,1]
	v_pk_fma_f32 v[226:227], v[206:207], v[226:227], v[26:27] op_sel:[1,0,0]
	v_pk_fma_f32 v[228:229], v[206:207], v[228:229], v[24:25] op_sel:[1,0,0]
	v_mul_f32_e32 v226, 0xbfb8aa3b, v226
	v_mul_f32_e32 v205, 0xbfb8aa3b, v228
	v_mul_f32_e32 v221, 0xbfb8aa3b, v229
	v_mul_f32_e32 v227, 0xbfb8aa3b, v227
	v_exp_f32_e32 v205, v205
	v_exp_f32_e32 v221, v221
	v_exp_f32_e32 v226, v226
	v_exp_f32_e32 v227, v227
	v_add_f32_e32 v205, 1.0, v205
	v_add_f32_e32 v221, 1.0, v221
	v_add_f32_e32 v228, 1.0, v226
	v_add_f32_e32 v229, 1.0, v227
	v_rcp_f32_e32 v226, v205
	v_rcp_f32_e32 v227, v221
	v_rcp_f32_e32 v228, v228
	v_rcp_f32_e32 v229, v229
	s_waitcnt vmcnt(1)
	v_lshlrev_b32_e32 v205, 16, v222
	v_and_b32_e32 v221, 0xffff0000, v222
	v_lshlrev_b32_e32 v230, 16, v223
	v_and_b32_e32 v231, 0xffff0000, v223
	v_sub_f32_e32 v231, v231, v206
	v_sub_f32_e32 v230, v230, v206
	v_sub_f32_e32 v233, v221, v206
	v_sub_f32_e32 v232, v205, v206
	v_pk_mul_f32 v[232:233], v[206:207], v[232:233] op_sel:[1,0]
	v_pk_mul_f32 v[230:231], v[206:207], v[230:231] op_sel:[1,0]
	s_waitcnt vmcnt(0)
	v_lshlrev_b32_e32 v222, 16, v224
	v_and_b32_e32 v223, 0xffff0000, v224
	v_lshlrev_b32_e32 v224, 16, v225
	v_and_b32_e32 v225, 0xffff0000, v225
	v_pk_fma_f32 v[230:231], v[18:19], v[230:231], v[22:23]
	v_pk_fma_f32 v[232:233], v[16:17], v[232:233], v[20:21]
	v_pk_fma_f32 v[224:225], v[228:229], v[224:225], v[230:231]
	v_pk_fma_f32 v[222:223], v[226:227], v[222:223], v[232:233]
	global_store_dwordx4 v[208:209], v[222:225], off offset:512
	global_load_dwordx2 v[222:223], v[210:211], off offset:288
	s_nop 0
	global_load_dwordx2 v[212:213], v[212:213], off offset:288
	v_pk_mul_f32 v[224:225], v[14:15], v[206:207] op_sel_hi:[1,0]
	v_pk_mul_f32 v[232:233], v[12:13], v[206:207] op_sel_hi:[1,0]
	v_pk_fma_f32 v[224:225], v[62:63], s[26:27], v[224:225] op_sel_hi:[1,0,1] neg_lo:[0,0,1] neg_hi:[0,0,1]
	v_pk_fma_f32 v[232:233], v[60:61], s[26:27], v[232:233] op_sel_hi:[1,0,1] neg_lo:[0,0,1] neg_hi:[0,0,1]
	v_pk_fma_f32 v[224:225], v[206:207], v[224:225], v[10:11] op_sel:[1,0,0]
	v_pk_fma_f32 v[232:233], v[206:207], v[232:233], v[8:9] op_sel:[1,0,0]
	v_mul_f32_e32 v224, 0xbfb8aa3b, v224
	v_mul_f32_e32 v205, 0xbfb8aa3b, v232
	v_mul_f32_e32 v221, 0xbfb8aa3b, v233
	v_mul_f32_e32 v225, 0xbfb8aa3b, v225
	v_exp_f32_e32 v205, v205
	v_exp_f32_e32 v221, v221
	v_exp_f32_e32 v224, v224
	v_exp_f32_e32 v225, v225
	v_add_f32_e32 v205, 1.0, v205
	v_add_f32_e32 v221, 1.0, v221
	v_add_f32_e32 v232, 1.0, v224
	v_add_f32_e32 v233, 1.0, v225
	v_add_u32_e32 v226, 0xa0, v204
	v_rcp_f32_e32 v224, v205
	v_rcp_f32_e32 v225, v221
	v_rcp_f32_e32 v232, v232
	v_rcp_f32_e32 v233, v233
	v_ashrrev_i32_e32 v227, 31, v226
	v_lshlrev_b64 v[210:211], 12, v[226:227]
	v_lshl_add_u64 v[228:229], v[210:211], 0, v[202:203]
	v_lshlrev_b64 v[230:231], 1, v[228:229]
	v_lshl_add_u64 v[210:211], s[12:13], 0, v[230:231]
	s_waitcnt vmcnt(1)
	v_lshlrev_b32_e32 v205, 16, v222
	v_and_b32_e32 v221, 0xffff0000, v222
	v_lshlrev_b32_e32 v234, 16, v223
	v_and_b32_e32 v235, 0xffff0000, v223
	v_sub_f32_e32 v235, v235, v206
	v_sub_f32_e32 v234, v234, v206
	v_sub_f32_e32 v237, v221, v206
	v_sub_f32_e32 v236, v205, v206
	v_pk_mul_f32 v[236:237], v[206:207], v[236:237] op_sel:[1,0]
	v_pk_mul_f32 v[206:207], v[206:207], v[234:235] op_sel:[1,0]
	s_waitcnt vmcnt(0)
	v_lshlrev_b32_e32 v222, 16, v212
	v_and_b32_e32 v223, 0xffff0000, v212
	v_lshlrev_b32_e32 v212, 16, v213
	v_and_b32_e32 v213, 0xffff0000, v213
	v_pk_fma_f32 v[206:207], v[2:3], v[206:207], v[6:7]
	v_pk_fma_f32 v[234:235], v[0:1], v[236:237], v[4:5]
	s_nop 0
	v_pk_fma_f32 v[222:223], v[224:225], v[222:223], v[234:235]
	v_pk_fma_f32 v[224:225], v[232:233], v[212:213], v[206:207]
	global_store_dwordx4 v[208:209], v[222:225], off offset:576
	v_lshl_add_u64 v[206:207], v[226:227], 3, s[0:1]
	v_lshl_add_u64 v[212:213], s[18:19], 0, v[230:231]
	global_load_dwordx2 v[222:223], v[210:211], off
	global_load_dwordx2 v[224:225], v[212:213], off
	s_nop 0
	global_load_dwordx2 v[206:207], v[206:207], off
	v_lshl_add_u64 v[208:209], v[228:229], 2, s[14:15]
	s_waitcnt vmcnt(2)
	v_lshlrev_b32_e32 v205, 16, v222
	v_and_b32_e32 v221, 0xffff0000, v222
	v_lshlrev_b32_e32 v230, 16, v223
	v_and_b32_e32 v231, 0xffff0000, v223
	s_waitcnt vmcnt(0)
	v_pk_mul_f32 v[222:223], v[178:179], v[206:207] op_sel_hi:[1,0]
	v_pk_mul_f32 v[226:227], v[176:177], v[206:207] op_sel_hi:[1,0]
	v_pk_fma_f32 v[222:223], v[70:71], s[26:27], v[222:223] op_sel_hi:[1,0,1] neg_lo:[0,0,1] neg_hi:[0,0,1]
	v_pk_fma_f32 v[226:227], v[68:69], s[26:27], v[226:227] op_sel_hi:[1,0,1] neg_lo:[0,0,1] neg_hi:[0,0,1]
	v_pk_fma_f32 v[222:223], v[206:207], v[222:223], v[190:191] op_sel:[1,0,0]
	v_pk_fma_f32 v[226:227], v[206:207], v[226:227], v[188:189] op_sel:[1,0,0]
	v_sub_f32_e32 v233, v221, v206
	v_sub_f32_e32 v232, v205, v206
	v_mul_f32_e32 v205, 0xbfb8aa3b, v226
	v_mul_f32_e32 v221, 0xbfb8aa3b, v227
	v_mul_f32_e32 v222, 0xbfb8aa3b, v222
	v_mul_f32_e32 v223, 0xbfb8aa3b, v223
	v_exp_f32_e32 v205, v205
	v_exp_f32_e32 v221, v221
	v_exp_f32_e32 v222, v222
	v_exp_f32_e32 v223, v223
	v_add_f32_e32 v205, 1.0, v205
	v_add_f32_e32 v221, 1.0, v221
	v_add_f32_e32 v226, 1.0, v222
	v_add_f32_e32 v227, 1.0, v223
	v_rcp_f32_e32 v222, v205
	v_rcp_f32_e32 v223, v221
	v_rcp_f32_e32 v226, v226
	v_rcp_f32_e32 v227, v227
	v_sub_f32_e32 v231, v231, v206
	v_sub_f32_e32 v230, v230, v206
	v_pk_mul_f32 v[232:233], v[206:207], v[232:233] op_sel:[1,0]
	v_pk_mul_f32 v[230:231], v[206:207], v[230:231] op_sel:[1,0]
	v_lshlrev_b32_e32 v228, 16, v224
	v_and_b32_e32 v229, 0xffff0000, v224
	v_lshlrev_b32_e32 v224, 16, v225
	v_and_b32_e32 v225, 0xffff0000, v225
	v_pk_fma_f32 v[230:231], v[186:187], v[230:231], v[182:183]
	v_pk_fma_f32 v[232:233], v[184:185], v[232:233], v[180:181]
	v_pk_fma_f32 v[224:225], v[226:227], v[224:225], v[230:231]
	v_pk_fma_f32 v[222:223], v[222:223], v[228:229], v[232:233]
	global_store_dwordx4 v[208:209], v[222:225], off
	global_load_dwordx2 v[222:223], v[210:211], off offset:32
	s_nop 0
	global_load_dwordx2 v[224:225], v[212:213], off offset:32
	v_pk_mul_f32 v[226:227], v[174:175], v[206:207] op_sel_hi:[1,0]
	v_pk_mul_f32 v[228:229], v[172:173], v[206:207] op_sel_hi:[1,0]
	v_pk_fma_f32 v[226:227], v[58:59], s[26:27], v[226:227] op_sel_hi:[1,0,1] neg_lo:[0,0,1] neg_hi:[0,0,1]
	v_pk_fma_f32 v[228:229], v[56:57], s[26:27], v[228:229] op_sel_hi:[1,0,1] neg_lo:[0,0,1] neg_hi:[0,0,1]
	v_pk_fma_f32 v[226:227], v[206:207], v[226:227], v[170:171] op_sel:[1,0,0]
	v_pk_fma_f32 v[228:229], v[206:207], v[228:229], v[168:169] op_sel:[1,0,0]
	v_mul_f32_e32 v226, 0xbfb8aa3b, v226
	v_mul_f32_e32 v205, 0xbfb8aa3b, v228
	v_mul_f32_e32 v221, 0xbfb8aa3b, v229
	v_mul_f32_e32 v227, 0xbfb8aa3b, v227
	v_exp_f32_e32 v205, v205
	v_exp_f32_e32 v221, v221
	v_exp_f32_e32 v226, v226
	v_exp_f32_e32 v227, v227
	v_add_f32_e32 v205, 1.0, v205
	v_add_f32_e32 v221, 1.0, v221
	v_add_f32_e32 v228, 1.0, v226
	v_add_f32_e32 v229, 1.0, v227
	v_rcp_f32_e32 v226, v205
	v_rcp_f32_e32 v227, v221
	v_rcp_f32_e32 v228, v228
	v_rcp_f32_e32 v229, v229
	s_waitcnt vmcnt(1)
	v_lshlrev_b32_e32 v205, 16, v222
	v_and_b32_e32 v221, 0xffff0000, v222
	v_lshlrev_b32_e32 v230, 16, v223
	v_and_b32_e32 v231, 0xffff0000, v223
	v_sub_f32_e32 v231, v231, v206
	v_sub_f32_e32 v230, v230, v206
	v_sub_f32_e32 v233, v221, v206
	v_sub_f32_e32 v232, v205, v206
	v_pk_mul_f32 v[232:233], v[206:207], v[232:233] op_sel:[1,0]
	v_pk_mul_f32 v[230:231], v[206:207], v[230:231] op_sel:[1,0]
	s_waitcnt vmcnt(0)
	v_lshlrev_b32_e32 v222, 16, v224
	v_and_b32_e32 v223, 0xffff0000, v224
	v_lshlrev_b32_e32 v224, 16, v225
	v_and_b32_e32 v225, 0xffff0000, v225
	v_pk_fma_f32 v[230:231], v[162:163], v[230:231], v[166:167]
	v_pk_fma_f32 v[232:233], v[160:161], v[232:233], v[164:165]
	v_pk_fma_f32 v[224:225], v[228:229], v[224:225], v[230:231]
	v_pk_fma_f32 v[222:223], v[226:227], v[222:223], v[232:233]
	global_store_dwordx4 v[208:209], v[222:225], off offset:64
	global_load_dwordx2 v[222:223], v[210:211], off offset:256
	s_nop 0
	global_load_dwordx2 v[224:225], v[212:213], off offset:256
	v_pk_mul_f32 v[226:227], v[30:31], v[206:207] op_sel_hi:[1,0]
	v_pk_mul_f32 v[228:229], v[28:29], v[206:207] op_sel_hi:[1,0]
	v_pk_fma_f32 v[226:227], v[50:51], s[26:27], v[226:227] op_sel_hi:[1,0,1] neg_lo:[0,0,1] neg_hi:[0,0,1]
	v_pk_fma_f32 v[228:229], v[48:49], s[26:27], v[228:229] op_sel_hi:[1,0,1] neg_lo:[0,0,1] neg_hi:[0,0,1]
	v_pk_fma_f32 v[226:227], v[206:207], v[226:227], v[26:27] op_sel:[1,0,0]
	v_pk_fma_f32 v[228:229], v[206:207], v[228:229], v[24:25] op_sel:[1,0,0]
	v_mul_f32_e32 v226, 0xbfb8aa3b, v226
	v_mul_f32_e32 v205, 0xbfb8aa3b, v228
	v_mul_f32_e32 v221, 0xbfb8aa3b, v229
	v_mul_f32_e32 v227, 0xbfb8aa3b, v227
	v_exp_f32_e32 v205, v205
	v_exp_f32_e32 v221, v221
	v_exp_f32_e32 v226, v226
	v_exp_f32_e32 v227, v227
	v_add_f32_e32 v205, 1.0, v205
	v_add_f32_e32 v221, 1.0, v221
	v_add_f32_e32 v228, 1.0, v226
	v_add_f32_e32 v229, 1.0, v227
	v_rcp_f32_e32 v226, v205
	v_rcp_f32_e32 v227, v221
	v_rcp_f32_e32 v228, v228
	v_rcp_f32_e32 v229, v229
	s_waitcnt vmcnt(1)
	v_lshlrev_b32_e32 v205, 16, v222
	v_and_b32_e32 v221, 0xffff0000, v222
	v_lshlrev_b32_e32 v230, 16, v223
	v_and_b32_e32 v231, 0xffff0000, v223
	v_sub_f32_e32 v231, v231, v206
	v_sub_f32_e32 v230, v230, v206
	v_sub_f32_e32 v233, v221, v206
	v_sub_f32_e32 v232, v205, v206
	v_pk_mul_f32 v[232:233], v[206:207], v[232:233] op_sel:[1,0]
	v_pk_mul_f32 v[230:231], v[206:207], v[230:231] op_sel:[1,0]
	s_waitcnt vmcnt(0)
	v_lshlrev_b32_e32 v222, 16, v224
	v_and_b32_e32 v223, 0xffff0000, v224
	v_lshlrev_b32_e32 v224, 16, v225
	v_and_b32_e32 v225, 0xffff0000, v225
	v_pk_fma_f32 v[230:231], v[18:19], v[230:231], v[22:23]
	v_pk_fma_f32 v[232:233], v[16:17], v[232:233], v[20:21]
	v_pk_fma_f32 v[224:225], v[228:229], v[224:225], v[230:231]
	v_pk_fma_f32 v[222:223], v[226:227], v[222:223], v[232:233]
	global_store_dwordx4 v[208:209], v[222:225], off offset:512
	global_load_dwordx2 v[222:223], v[210:211], off offset:288
	s_nop 0
	global_load_dwordx2 v[212:213], v[212:213], off offset:288
	v_add_u32_e32 v224, 0xb0, v204
	v_ashrrev_i32_e32 v225, 31, v224
	v_lshlrev_b64 v[204:205], 12, v[224:225]
	v_lshl_add_u64 v[226:227], v[204:205], 0, v[202:203]
	v_pk_mul_f32 v[204:205], v[14:15], v[206:207] op_sel_hi:[1,0]
	v_pk_mul_f32 v[230:231], v[12:13], v[206:207] op_sel_hi:[1,0]
	v_pk_fma_f32 v[204:205], v[42:43], s[26:27], v[204:205] op_sel_hi:[1,0,1] neg_lo:[0,0,1] neg_hi:[0,0,1]
	v_pk_fma_f32 v[230:231], v[40:41], s[26:27], v[230:231] op_sel_hi:[1,0,1] neg_lo:[0,0,1] neg_hi:[0,0,1]
	v_pk_fma_f32 v[204:205], v[206:207], v[204:205], v[10:11] op_sel:[1,0,0]
	v_pk_fma_f32 v[230:231], v[206:207], v[230:231], v[8:9] op_sel:[1,0,0]
	v_mul_f32_e32 v204, 0xbfb8aa3b, v204
	v_mul_f32_e32 v221, 0xbfb8aa3b, v230
	v_mul_f32_e32 v230, 0xbfb8aa3b, v231
	v_mul_f32_e32 v205, 0xbfb8aa3b, v205
	v_exp_f32_e32 v221, v221
	v_exp_f32_e32 v230, v230
	v_exp_f32_e32 v204, v204
	v_exp_f32_e32 v205, v205
	v_add_f32_e32 v221, 1.0, v221
	v_add_f32_e32 v230, 1.0, v230
	v_add_f32_e32 v231, 1.0, v204
	v_add_f32_e32 v232, 1.0, v205
	v_rcp_f32_e32 v204, v221
	v_rcp_f32_e32 v205, v230
	v_rcp_f32_e32 v230, v231
	v_rcp_f32_e32 v231, v232
	v_lshlrev_b64 v[228:229], 1, v[226:227]
	v_lshl_add_u64 v[210:211], s[12:13], 0, v[228:229]
	s_waitcnt vmcnt(1)
	v_lshlrev_b32_e32 v221, 16, v222
	v_and_b32_e32 v234, 0xffff0000, v222
	v_lshlrev_b32_e32 v232, 16, v223
	v_and_b32_e32 v233, 0xffff0000, v223
	v_sub_f32_e32 v233, v233, v206
	v_sub_f32_e32 v232, v232, v206
	v_sub_f32_e32 v235, v234, v206
	v_sub_f32_e32 v234, v221, v206
	v_pk_mul_f32 v[234:235], v[206:207], v[234:235] op_sel:[1,0]
	v_pk_mul_f32 v[206:207], v[206:207], v[232:233] op_sel:[1,0]
	s_waitcnt vmcnt(0)
	v_lshlrev_b32_e32 v222, 16, v212
	v_and_b32_e32 v223, 0xffff0000, v212
	v_lshlrev_b32_e32 v212, 16, v213
	v_and_b32_e32 v213, 0xffff0000, v213
	v_pk_fma_f32 v[206:207], v[2:3], v[206:207], v[6:7]
	v_pk_fma_f32 v[232:233], v[0:1], v[234:235], v[4:5]
	v_pk_fma_f32 v[206:207], v[230:231], v[212:213], v[206:207]
	v_pk_fma_f32 v[204:205], v[204:205], v[222:223], v[232:233]
	global_store_dwordx4 v[208:209], v[204:207], off offset:576
	v_lshl_add_u64 v[208:209], s[18:19], 0, v[228:229]
	global_load_dwordx2 v[212:213], v[210:211], off
	v_lshl_add_u64 v[204:205], v[224:225], 3, s[0:1]
	global_load_dwordx2 v[222:223], v[208:209], off
	s_nop 0
	global_load_dwordx2 v[204:205], v[204:205], off
	v_lshl_add_u64 v[206:207], v[226:227], 2, s[14:15]
	s_waitcnt vmcnt(2)
	v_lshlrev_b32_e32 v221, 16, v212
	v_and_b32_e32 v226, 0xffff0000, v212
	s_waitcnt vmcnt(0)
	v_pk_mul_f32 v[178:179], v[178:179], v[204:205] op_sel_hi:[1,0]
	v_pk_mul_f32 v[176:177], v[176:177], v[204:205] op_sel_hi:[1,0]
	v_pk_fma_f32 v[178:179], v[54:55], s[26:27], v[178:179] op_sel_hi:[1,0,1] neg_lo:[0,0,1] neg_hi:[0,0,1]
	v_pk_fma_f32 v[176:177], v[52:53], s[26:27], v[176:177] op_sel_hi:[1,0,1] neg_lo:[0,0,1] neg_hi:[0,0,1]
	v_pk_fma_f32 v[178:179], v[204:205], v[178:179], v[190:191] op_sel:[1,0,0]
	v_pk_fma_f32 v[176:177], v[204:205], v[176:177], v[188:189] op_sel:[1,0,0]
	v_mul_f32_e32 v178, 0xbfb8aa3b, v178
	v_mul_f32_e32 v176, 0xbfb8aa3b, v176
	v_mul_f32_e32 v177, 0xbfb8aa3b, v177
	v_mul_f32_e32 v179, 0xbfb8aa3b, v179
	v_exp_f32_e32 v176, v176
	v_exp_f32_e32 v177, v177
	v_exp_f32_e32 v178, v178
	v_exp_f32_e32 v179, v179
	v_add_f32_e32 v176, 1.0, v176
	v_add_f32_e32 v177, 1.0, v177
	v_add_f32_e32 v178, 1.0, v178
	v_add_f32_e32 v179, 1.0, v179
	v_lshlrev_b32_e32 v224, 16, v213
	v_and_b32_e32 v225, 0xffff0000, v213
	v_rcp_f32_e32 v176, v176
	v_rcp_f32_e32 v177, v177
	v_rcp_f32_e32 v178, v178
	v_rcp_f32_e32 v179, v179
	v_sub_f32_e32 v225, v225, v204
	v_sub_f32_e32 v224, v224, v204
	v_sub_f32_e32 v227, v226, v204
	v_sub_f32_e32 v226, v221, v204
	v_pk_mul_f32 v[226:227], v[204:205], v[226:227] op_sel:[1,0]
	v_pk_mul_f32 v[224:225], v[204:205], v[224:225] op_sel:[1,0]
	v_lshlrev_b32_e32 v212, 16, v222
	v_and_b32_e32 v213, 0xffff0000, v222
	v_lshlrev_b32_e32 v222, 16, v223
	v_and_b32_e32 v223, 0xffff0000, v223
	v_pk_fma_f32 v[182:183], v[186:187], v[224:225], v[182:183]
	v_pk_fma_f32 v[180:181], v[184:185], v[226:227], v[180:181]
	v_pk_fma_f32 v[178:179], v[178:179], v[222:223], v[182:183]
	v_pk_fma_f32 v[176:177], v[176:177], v[212:213], v[180:181]
	global_store_dwordx4 v[206:207], v[176:179], off
	global_load_dwordx2 v[176:177], v[210:211], off offset:32
	s_nop 0
	global_load_dwordx2 v[178:179], v[208:209], off offset:32
	v_pk_mul_f32 v[174:175], v[174:175], v[204:205] op_sel_hi:[1,0]
	v_pk_mul_f32 v[172:173], v[172:173], v[204:205] op_sel_hi:[1,0]
	v_pk_fma_f32 v[174:175], v[46:47], s[26:27], v[174:175] op_sel_hi:[1,0,1] neg_lo:[0,0,1] neg_hi:[0,0,1]
	v_pk_fma_f32 v[172:173], v[44:45], s[26:27], v[172:173] op_sel_hi:[1,0,1] neg_lo:[0,0,1] neg_hi:[0,0,1]
	v_pk_fma_f32 v[170:171], v[204:205], v[174:175], v[170:171] op_sel:[1,0,0]
	v_pk_fma_f32 v[168:169], v[204:205], v[172:173], v[168:169] op_sel:[1,0,0]
	v_mul_f32_e32 v170, 0xbfb8aa3b, v170
	v_mul_f32_e32 v168, 0xbfb8aa3b, v168
	v_mul_f32_e32 v169, 0xbfb8aa3b, v169
	v_mul_f32_e32 v171, 0xbfb8aa3b, v171
	v_exp_f32_e32 v168, v168
	v_exp_f32_e32 v169, v169
	v_exp_f32_e32 v170, v170
	v_exp_f32_e32 v171, v171
	v_add_f32_e32 v168, 1.0, v168
	v_add_f32_e32 v169, 1.0, v169
	v_add_f32_e32 v170, 1.0, v170
	v_add_f32_e32 v171, 1.0, v171
	v_rcp_f32_e32 v168, v168
	v_rcp_f32_e32 v169, v169
	v_rcp_f32_e32 v170, v170
	v_rcp_f32_e32 v171, v171
	v_pk_mul_f32 v[30:31], v[30:31], v[204:205] op_sel_hi:[1,0]
	v_pk_mul_f32 v[28:29], v[28:29], v[204:205] op_sel_hi:[1,0]
	v_pk_fma_f32 v[30:31], v[38:39], s[26:27], v[30:31] op_sel_hi:[1,0,1] neg_lo:[0,0,1] neg_hi:[0,0,1]
	v_pk_fma_f32 v[28:29], v[36:37], s[26:27], v[28:29] op_sel_hi:[1,0,1] neg_lo:[0,0,1] neg_hi:[0,0,1]
	v_pk_fma_f32 v[26:27], v[204:205], v[30:31], v[26:27] op_sel:[1,0,0]
	v_pk_fma_f32 v[24:25], v[204:205], v[28:29], v[24:25] op_sel:[1,0,0]
	v_mul_f32_e32 v26, 0xbfb8aa3b, v26
	v_mul_f32_e32 v24, 0xbfb8aa3b, v24
	v_mul_f32_e32 v25, 0xbfb8aa3b, v25
	v_mul_f32_e32 v27, 0xbfb8aa3b, v27
	v_exp_f32_e32 v24, v24
	v_exp_f32_e32 v25, v25
	v_exp_f32_e32 v26, v26
	v_exp_f32_e32 v27, v27
	v_add_f32_e32 v24, 1.0, v24
	v_add_f32_e32 v25, 1.0, v25
	v_add_f32_e32 v26, 1.0, v26
	v_add_f32_e32 v27, 1.0, v27
	v_rcp_f32_e32 v24, v24
	v_rcp_f32_e32 v25, v25
	v_rcp_f32_e32 v26, v26
	v_rcp_f32_e32 v27, v27
	v_pk_mul_f32 v[14:15], v[14:15], v[204:205] op_sel_hi:[1,0]
	v_pk_mul_f32 v[12:13], v[12:13], v[204:205] op_sel_hi:[1,0]
	v_pk_fma_f32 v[14:15], v[34:35], s[26:27], v[14:15] op_sel_hi:[1,0,1] neg_lo:[0,0,1] neg_hi:[0,0,1]
	v_pk_fma_f32 v[12:13], v[32:33], s[26:27], v[12:13] op_sel_hi:[1,0,1] neg_lo:[0,0,1] neg_hi:[0,0,1]
	v_pk_fma_f32 v[10:11], v[204:205], v[14:15], v[10:11] op_sel:[1,0,0]
	v_pk_fma_f32 v[8:9], v[204:205], v[12:13], v[8:9] op_sel:[1,0,0]
	v_mul_f32_e32 v10, 0xbfb8aa3b, v10
	v_mul_f32_e32 v8, 0xbfb8aa3b, v8
	v_mul_f32_e32 v9, 0xbfb8aa3b, v9
	v_mul_f32_e32 v11, 0xbfb8aa3b, v11
	v_exp_f32_e32 v8, v8
	v_exp_f32_e32 v9, v9
	v_exp_f32_e32 v10, v10
	v_exp_f32_e32 v11, v11
	v_add_f32_e32 v8, 1.0, v8
	v_add_f32_e32 v9, 1.0, v9
	v_add_f32_e32 v10, 1.0, v10
	v_add_f32_e32 v11, 1.0, v11
	v_rcp_f32_e32 v8, v8
	v_rcp_f32_e32 v9, v9
	v_rcp_f32_e32 v10, v10
	v_rcp_f32_e32 v11, v11
	s_waitcnt vmcnt(1)
	v_lshlrev_b32_e32 v180, 16, v176
	v_and_b32_e32 v181, 0xffff0000, v176
	v_lshlrev_b32_e32 v176, 16, v177
	v_and_b32_e32 v177, 0xffff0000, v177
	s_waitcnt vmcnt(0)
	v_lshlrev_b32_e32 v172, 16, v178
	v_and_b32_e32 v173, 0xffff0000, v178
	v_lshlrev_b32_e32 v174, 16, v179
	v_and_b32_e32 v175, 0xffff0000, v179
	v_sub_f32_e32 v177, v177, v204
	v_sub_f32_e32 v176, v176, v204
	v_sub_f32_e32 v179, v181, v204
	v_sub_f32_e32 v178, v180, v204
	v_pk_mul_f32 v[178:179], v[204:205], v[178:179] op_sel:[1,0]
	v_pk_mul_f32 v[176:177], v[204:205], v[176:177] op_sel:[1,0]
	v_pk_fma_f32 v[160:161], v[160:161], v[178:179], v[164:165]
	v_pk_fma_f32 v[162:163], v[162:163], v[176:177], v[166:167]
	v_pk_fma_f32 v[160:161], v[168:169], v[172:173], v[160:161]
	v_pk_fma_f32 v[162:163], v[170:171], v[174:175], v[162:163]
	global_store_dwordx4 v[206:207], v[160:163], off offset:64
	global_load_dwordx2 v[160:161], v[210:211], off offset:256
	s_nop 0
	global_load_dwordx2 v[162:163], v[208:209], off offset:256
	s_waitcnt vmcnt(1)
	v_lshlrev_b32_e32 v164, 16, v160
	v_and_b32_e32 v165, 0xffff0000, v160
	v_lshlrev_b32_e32 v160, 16, v161
	v_and_b32_e32 v161, 0xffff0000, v161
	s_waitcnt vmcnt(0)
	v_lshlrev_b32_e32 v28, 16, v162
	v_and_b32_e32 v29, 0xffff0000, v162
	v_lshlrev_b32_e32 v30, 16, v163
	v_and_b32_e32 v31, 0xffff0000, v163
	v_sub_f32_e32 v161, v161, v204
	v_sub_f32_e32 v160, v160, v204
	v_sub_f32_e32 v163, v165, v204
	v_sub_f32_e32 v162, v164, v204
	v_pk_mul_f32 v[162:163], v[204:205], v[162:163] op_sel:[1,0]
	v_pk_mul_f32 v[160:161], v[204:205], v[160:161] op_sel:[1,0]
	v_pk_fma_f32 v[16:17], v[16:17], v[162:163], v[20:21]
	v_pk_fma_f32 v[18:19], v[18:19], v[160:161], v[22:23]
	v_pk_fma_f32 v[16:17], v[24:25], v[28:29], v[16:17]
	v_pk_fma_f32 v[18:19], v[26:27], v[30:31], v[18:19]
	global_store_dwordx4 v[206:207], v[16:19], off offset:512
	global_load_dwordx2 v[16:17], v[210:211], off offset:288
	s_nop 0
	global_load_dwordx2 v[18:19], v[208:209], off offset:288
	s_waitcnt vmcnt(1)
	v_lshlrev_b32_e32 v20, 16, v16
	v_and_b32_e32 v21, 0xffff0000, v16
	v_lshlrev_b32_e32 v16, 16, v17
	v_and_b32_e32 v17, 0xffff0000, v17
	s_waitcnt vmcnt(0)
	v_lshlrev_b32_e32 v12, 16, v18
	v_and_b32_e32 v13, 0xffff0000, v18
	v_lshlrev_b32_e32 v14, 16, v19
	v_and_b32_e32 v15, 0xffff0000, v19
	v_sub_f32_e32 v17, v17, v204
	v_sub_f32_e32 v16, v16, v204
	v_sub_f32_e32 v19, v21, v204
	v_sub_f32_e32 v18, v20, v204
	v_pk_mul_f32 v[18:19], v[204:205], v[18:19] op_sel:[1,0]
	v_pk_mul_f32 v[16:17], v[204:205], v[16:17] op_sel:[1,0]
	v_pk_fma_f32 v[0:1], v[0:1], v[18:19], v[4:5]
	v_pk_fma_f32 v[2:3], v[2:3], v[16:17], v[6:7]
	v_pk_fma_f32 v[0:1], v[8:9], v[12:13], v[0:1]
	v_pk_fma_f32 v[2:3], v[10:11], v[14:15], v[2:3]
	global_store_dwordx4 v[206:207], v[0:3], off offset:576
	s_cbranch_execz .LBB0_1608
